# pool phase: loads whose row addresses are already known are issued together at each window-group start (were one load per round trip)
# speedup vs baseline: 1.0061x; 1.0015x over previous
; __device__ __forceinline__ unsigned pk2(float lo, float hi) { unsigned r; asm("v_cvt_pk_bf16_f32 %0, %1, %2" : "=v"(r) : "v"(lo), "v"(hi)); return r; }
; __device__ __forceinline__ float bflo(unsigned u) { return __uint_as_float(u << 16); }
; __device__ __forceinline__ float bfhi(unsigned u) { return __uint_as_float(u & 0xFFFF0000u); }
; template <int J> __device__ __forceinline__ void pool_group(const bf16_t* hbuf, bf16_t* pl, int c0, int lane) {
;     constexpr int W = 2 << J, H = W >> 1, NR = 8 + W - 1;
;     u32x2 raw[NR];
; #pragma unroll
;     for (int k = 0; k < NR; ++k) { const int tt = c0 - H + k; const bool ok = tt >= 0 && tt < SEQ; const int tc = ok ? tt : c0;
;         raw[k] = *((const u32x2*)(hbuf + (size_t)tc * D + 256 * J) + lane); if (!ok) raw[k] = (u32x2){0u, 0u}; }
;     float s0 = 0.f, s1 = 0.f, s2 = 0.f, s3 = 0.f;
; #pragma unroll
;     for (int k = 0; k < W; ++k) { s0 += bflo(raw[k].x); s1 += bfhi(raw[k].x); s2 += bflo(raw[k].y); s3 += bfhi(raw[k].y); }
; #pragma unroll
;     for (int i = 0; i < 8; ++i) {
;         const int t = c0 + i; int lo = t - H, hi = t + H - 1; lo = lo < 0 ? 0 : lo; hi = hi > SEQ - 1 ? SEQ - 1 : hi;
;         const float ic = 1.f / (float)(hi - lo + 1);
;         const u32x2 self = raw[i + H];
;         u32x2 o; o.x = pk2(s0 * ic - bflo(self.x), s1 * ic - bfhi(self.x)); o.y = pk2(s2 * ic - bflo(self.y), s3 * ic - bfhi(self.y));
;         *((u32x2*)(pl + ((size_t)J * SEQ + t) * 256) + lane) = o;
;         if (i < 7) { s0 += bflo(raw[i + W].x) - bflo(raw[i].x); s1 += bfhi(raw[i + W].x) - bfhi(raw[i].x); s2 += bflo(raw[i + W].y) - bflo(raw[i].y); s3 += bfhi(raw[i + W].y) - bfhi(raw[i].y); }
;     }
; }
.LBB0_327:
	v_add_u32_e32 v3, -1, v2
	v_cmp_gt_u32_e64 s[16:17], s33, v3
	s_mov_b32 s2, 0x1c9b9000
	v_cmp_gt_u32_e64 s[0:1], s33, v2
	v_cndmask_b32_e64 v10, v2, v3, s[16:17]
	v_ashrrev_i32_e32 v11, 31, v10
	v_lshlrev_b64 v[10:11], 11, v[10:11]
	v_lshl_add_u64 v[12:13], v[4:5], 0, v[10:11]
	global_load_dwordx2 v[10:11], v[12:13], off
	s_waitcnt vmcnt(0)
	v_add_u32_e32 v45, 1, v2
	v_add_u32_e32 v44, 2, v2
	v_add_u32_e32 v46, 3, v2
	v_add_u32_e32 v47, 4, v2
	v_add_u32_e32 v48, 5, v2
	v_add_u32_e32 v49, 6, v2
	v_add_u32_e32 v3, 7, v2
	v_max_i32_e32 v32, 1, v2
	v_max_i32_e32 v63, 1, v45
	v_min_i32_e32 v64, 0x3fff, v45
	v_sub_u32_e32 v63, v64, v63
	v_add_u32_e32 v63, 2, v63
	v_cvt_f32_i32_e32 v63, v63
	v_min_i32_e32 v69, 0x3ffe, v2
	v_min_i32_e32 v74, 0x3ffe, v45
	v_min_i32_e32 v79, 0x3ffe, v44
	v_max_i32_e32 v84, 4, v2
	v_min_i32_e32 v85, 0x3ffc, v2
	v_sub_u32_e32 v84, v85, v84
	v_add_u32_e32 v84, 8, v84
	v_cvt_f32_i32_e32 v84, v84
	v_min_i32_e32 v90, 0x3ffc, v45
	v_min_i32_e32 v95, 0x3ffc, v44
	v_min_i32_e32 v105, 0x3ffc, v47
	v_min_i32_e32 v110, 0x3ffc, v48
	v_min_i32_e32 v115, 0x3ffc, v49
	s_waitcnt vmcnt(0)
	v_cndmask_b32_e64 v33, 0, v11, s[16:17]
	v_cndmask_b32_e64 v34, 0, v10, s[16:17]
	v_lshl_add_u64 v[10:11], v[8:9], 0, v[0:1]
	v_add_co_u32_e32 v14, vcc, s2, v10
	v_div_scale_f32 v64, s[2:3], v63, v63, 1.0
	s_nop 0
	v_addc_co_u32_e32 v15, vcc, 0, v11, vcc
	global_load_dwordx2 v[10:11], v[14:15], off
	v_rcp_f32_e32 v65, v64
	v_lshlrev_b32_e32 v60, 16, v33
	v_and_b32_e32 v33, 0xffff0000, v33
	v_add_f32_e32 v61, 0, v60
	v_fma_f32 v66, -v64, v65, 1.0
	v_fmac_f32_e32 v65, v66, v65
	v_lshl_add_u64 v[8:9], v[8:9], 0, s[38:39]
	s_waitcnt vmcnt(0)
	v_cndmask_b32_e64 v36, 0, v10, s[0:1]
	v_cndmask_b32_e64 v10, v2, v45, s[0:1]
	v_cndmask_b32_e64 v35, 0, v11, s[0:1]
	v_ashrrev_i32_e32 v11, 31, v10
	v_lshlrev_b64 v[10:11], 11, v[10:11]
	v_lshl_add_u64 v[16:17], v[4:5], 0, v[10:11]
	v_cndmask_b32_e64 v10, v2, v44, s[0:1]
	v_ashrrev_i32_e32 v11, 31, v10
	v_lshlrev_b64 v[10:11], 11, v[10:11]
	v_lshl_add_u64 v[18:19], v[4:5], 0, v[10:11]
	global_load_dwordx2 v[30:31], v[16:17], off
	global_load_dwordx2 v[10:11], v[18:19], off
	s_waitcnt vmcnt(1)
	v_cndmask_b32_e64 v30, 0, v30, s[0:1]
	s_waitcnt vmcnt(0)
	v_cndmask_b32_e64 v38, 0, v10, s[0:1]
	v_cndmask_b32_e64 v10, v2, v46, s[0:1]
	v_cndmask_b32_e64 v37, 0, v11, s[0:1]
	v_ashrrev_i32_e32 v11, 31, v10
	v_lshlrev_b64 v[10:11], 11, v[10:11]
	v_lshl_add_u64 v[20:21], v[4:5], 0, v[10:11]
	global_load_dwordx2 v[10:11], v[20:21], off
	v_and_b32_e32 v58, 0xffff0000, v30
	v_cndmask_b32_e64 v31, 0, v31, s[0:1]
	v_lshlrev_b32_e32 v59, 16, v31
	v_and_b32_e32 v62, 0xffff0000, v31
	v_add_f32_e32 v31, 0, v33
	v_sub_f32_e32 v60, v59, v60
	v_sub_f32_e32 v33, v62, v33
	s_waitcnt vmcnt(0)
	v_cndmask_b32_e64 v40, 0, v10, s[0:1]
	v_cndmask_b32_e64 v10, v2, v47, s[0:1]
	v_cndmask_b32_e64 v39, 0, v11, s[0:1]
	v_ashrrev_i32_e32 v11, 31, v10
	v_lshlrev_b64 v[10:11], 11, v[10:11]
	v_lshl_add_u64 v[22:23], v[4:5], 0, v[10:11]
	global_load_dwordx2 v[10:11], v[22:23], off
	s_waitcnt vmcnt(0)
	v_cndmask_b32_e64 v42, 0, v10, s[0:1]
	v_cndmask_b32_e64 v10, v2, v48, s[0:1]
	v_cndmask_b32_e64 v41, 0, v11, s[0:1]
	v_ashrrev_i32_e32 v11, 31, v10
	v_lshlrev_b64 v[10:11], 11, v[10:11]
	v_lshl_add_u64 v[24:25], v[4:5], 0, v[10:11]
	global_load_dwordx2 v[10:11], v[24:25], off
	s_waitcnt vmcnt(0)
	v_cndmask_b32_e64 v50, 0, v10, s[0:1]
	v_cndmask_b32_e64 v10, v2, v49, s[0:1]
	v_cndmask_b32_e64 v43, 0, v11, s[0:1]
	v_ashrrev_i32_e32 v11, 31, v10
	v_lshlrev_b64 v[10:11], 11, v[10:11]
	v_lshl_add_u64 v[26:27], v[4:5], 0, v[10:11]
	global_load_dwordx2 v[10:11], v[26:27], off
	s_waitcnt vmcnt(0)
	v_cndmask_b32_e64 v52, 0, v10, s[0:1]
	v_cndmask_b32_e64 v10, v2, v3, s[0:1]
	v_cndmask_b32_e64 v51, 0, v11, s[0:1]
	v_ashrrev_i32_e32 v11, 31, v10
	v_lshlrev_b64 v[10:11], 11, v[10:11]
	v_lshl_add_u64 v[28:29], v[4:5], 0, v[10:11]
	global_load_dwordx2 v[10:11], v[28:29], off
	s_waitcnt vmcnt(0)
	v_cndmask_b32_e64 v53, 0, v10, s[0:1]
	v_sub_u32_e32 v10, v44, v32
	v_cvt_f32_i32_e32 v10, v10
	v_cndmask_b32_e64 v54, 0, v11, s[0:1]
	v_div_scale_f32 v11, s[2:3], v10, v10, 1.0
	v_rcp_f32_e32 v32, v11
	s_mov_b32 s2, 0x4e7b9000
	v_fma_f32 v55, -v11, v32, 1.0
	v_fmac_f32_e32 v32, v55, v32
	v_div_scale_f32 v55, vcc, 1.0, v10, 1.0
	v_mul_f32_e32 v56, v55, v32
	v_fma_f32 v57, -v11, v56, v55
	v_fmac_f32_e32 v56, v57, v32
	v_fma_f32 v11, -v11, v56, v55
	v_div_fmas_f32 v11, v11, v32, v56
	v_div_scale_f32 v66, vcc, 1.0, v63, 1.0
	v_mul_f32_e32 v67, v66, v65
	v_fma_f32 v68, -v64, v67, v66
	v_fmac_f32_e32 v67, v68, v65
	v_fma_f32 v64, -v64, v67, v66
	v_lshlrev_b32_e32 v55, 16, v34
	v_div_fmas_f32 v64, v64, v65, v67
	v_lshlrev_b32_e32 v56, 16, v30
	v_add_f32_e32 v57, 0, v55
	v_and_b32_e32 v34, 0xffff0000, v34
	v_div_fixup_f32 v63, v64, v63, 1.0
	v_lshlrev_b32_e32 v64, 16, v36
	v_div_fixup_f32 v32, v11, v10, 1.0
	v_sub_f32_e32 v55, v56, v55
	v_add_f32_e32 v30, 0, v34
	v_lshlrev_b32_e32 v65, 16, v38
	v_add_f32_e32 v57, v57, v64
	v_and_b32_e32 v36, 0xffff0000, v36
	v_fma_f32 v66, v32, v57, -v64
	v_add_f32_e32 v55, v57, v55
	v_sub_f32_e32 v64, v65, v64
	v_add_f32_e32 v30, v30, v36
	v_sub_f32_e32 v34, v58, v34
	v_fma_f32 v57, v63, v55, -v56
	v_add_f32_e32 v55, v55, v64
	v_and_b32_e32 v38, 0xffff0000, v38
	v_fma_f32 v64, v32, v30, -v36
	v_add_f32_e32 v34, v30, v34
	v_cvt_pk_bf16_f32 v30, v66, v64
	v_sub_f32_e32 v36, v38, v36
	v_lshlrev_b32_e32 v64, 16, v35
	v_and_b32_e32 v35, 0xffff0000, v35
	v_fma_f32 v67, v63, v34, -v58
	v_add_f32_e32 v34, v34, v36
	v_lshlrev_b32_e32 v36, 16, v37
	v_add_f32_e32 v61, v61, v64
	v_add_f32_e32 v31, v31, v35
	v_lshl_add_u64 v[10:11], v[6:7], 0, v[0:1]
; __device__ __forceinline__ unsigned pk2(float lo, float hi) { unsigned r; asm("v_cvt_pk_bf16_f32 %0, %1, %2" : "=v"(r) : "v"(lo), "v"(hi)); return r; }
; __device__ __forceinline__ float bflo(unsigned u) { return __uint_as_float(u << 16); }
; __device__ __forceinline__ float bfhi(unsigned u) { return __uint_as_float(u & 0xFFFF0000u); }
; template <int J> __device__ __forceinline__ void pool_group(const bf16_t* hbuf, bf16_t* pl, int c0, int lane) {
;     ...
;     for (int i = 0; i < 8; ++i) {
;         const int t = c0 + i; int lo = t - H, hi = t + H - 1; lo = lo < 0 ? 0 : lo; hi = hi > SEQ - 1 ? SEQ - 1 : hi;
;         const float ic = 1.f / (float)(hi - lo + 1);
;         const u32x2 self = raw[i + H];
;         u32x2 o; o.x = pk2(s0 * ic - bflo(self.x), s1 * ic - bfhi(self.x)); o.y = pk2(s2 * ic - bflo(self.y), s3 * ic - bfhi(self.y));
;         *((u32x2*)(pl + ((size_t)J * SEQ + t) * 256) + lane) = o;
;         if (i < 7) { s0 += bflo(raw[i + W].x) - bflo(raw[i].x); s1 += bfhi(raw[i + W].x) - bfhi(raw[i].x); s2 += bflo(raw[i + W].y) - bflo(raw[i].y); s3 += bfhi(raw[i + W].y) - bfhi(raw[i].y); }
	v_fma_f32 v66, v32, v61, -v64
	v_add_f32_e32 v60, v61, v60
	v_sub_f32_e32 v64, v36, v64
	v_fma_f32 v32, v32, v31, -v35
	v_fma_f32 v61, v63, v60, -v59
	v_add_f32_e32 v60, v60, v64
	v_add_f32_e32 v64, v31, v33
	v_cvt_pk_bf16_f32 v31, v66, v32
	v_add_co_u32_e32 v32, vcc, s2, v10
	v_and_b32_e32 v37, 0xffff0000, v37
	s_nop 0
	v_addc_co_u32_e32 v33, vcc, 0, v11, vcc
	global_store_dwordx2 v[32:33], v[30:31], off
	v_cvt_pk_bf16_f32 v30, v57, v67
	v_fma_f32 v63, v63, v64, -v62
	v_cvt_pk_bf16_f32 v31, v61, v63
	global_store_dwordx2 v[32:33], v[30:31], off offset:512
	v_sub_f32_e32 v30, v37, v35
	v_add_f32_e32 v35, v64, v30
	v_max_i32_e32 v30, 1, v44
	v_min_i32_e32 v31, 0x3fff, v44
	v_sub_u32_e32 v30, v31, v30
	v_add_u32_e32 v30, 2, v30
	v_cvt_f32_i32_e32 v30, v30
	v_max_i32_e32 v68, 2, v2
	v_sub_u32_e32 v68, v69, v68
	v_add_u32_e32 v68, 4, v68
	v_div_scale_f32 v31, s[2:3], v30, v30, 1.0
	v_rcp_f32_e32 v57, v31
	v_cvt_f32_i32_e32 v68, v68
	v_lshl_add_u64 v[6:7], v[6:7], 0, s[42:43]
	v_fma_f32 v61, -v31, v57, 1.0
	v_fmac_f32_e32 v57, v61, v57
	v_div_scale_f32 v61, vcc, 1.0, v30, 1.0
	v_mul_f32_e32 v63, v61, v57
	v_fma_f32 v64, -v31, v63, v61
	v_fmac_f32_e32 v63, v64, v57
	v_fma_f32 v31, -v31, v63, v61
	v_div_fmas_f32 v31, v31, v57, v63
	v_div_fixup_f32 v31, v31, v30, 1.0
	v_fma_f32 v30, v31, v55, -v65
	v_fma_f32 v57, v31, v34, -v38
	v_cvt_pk_bf16_f32 v30, v30, v57
	v_fma_f32 v57, v31, v60, -v36
	v_fma_f32 v31, v31, v35, -v37
	v_cvt_pk_bf16_f32 v31, v57, v31
	global_store_dwordx2 v[32:33], v[30:31], off offset:1024
	v_max_i32_e32 v30, 1, v46
	v_min_i32_e32 v31, 0x3fff, v46
	v_sub_u32_e32 v30, v31, v30
	v_add_u32_e32 v30, 2, v30
	v_cvt_f32_i32_e32 v30, v30
	v_div_scale_f32 v69, s[2:3], v68, v68, 1.0
	v_rcp_f32_e32 v70, v69
	v_div_scale_f32 v31, s[2:3], v30, v30, 1.0
	v_rcp_f32_e32 v57, v31
	v_fma_f32 v71, -v69, v70, 1.0
	v_fmac_f32_e32 v70, v71, v70
	v_fma_f32 v61, -v31, v57, 1.0
	v_fmac_f32_e32 v57, v61, v57
	v_div_scale_f32 v61, vcc, 1.0, v30, 1.0
	v_mul_f32_e32 v63, v61, v57
	v_fma_f32 v64, -v31, v63, v61
	v_fmac_f32_e32 v63, v64, v57
	v_fma_f32 v31, -v31, v63, v61
	v_div_fmas_f32 v31, v31, v57, v63
	v_div_fixup_f32 v31, v31, v30, 1.0
	v_max_i32_e32 v30, 1, v47
	v_min_i32_e32 v57, 0x3fff, v47
	v_sub_u32_e32 v30, v57, v30
	v_add_u32_e32 v30, 2, v30
	v_cvt_f32_i32_e32 v30, v30
	v_div_scale_f32 v57, s[2:3], v30, v30, 1.0
	v_rcp_f32_e32 v61, v57
	s_nop 0
	v_fma_f32 v63, -v57, v61, 1.0
	v_fmac_f32_e32 v61, v63, v61
	v_div_scale_f32 v63, vcc, 1.0, v30, 1.0
	v_mul_f32_e32 v64, v63, v61
	v_fma_f32 v66, -v57, v64, v63
	v_fmac_f32_e32 v64, v66, v61
	v_fma_f32 v57, -v57, v64, v63
	v_div_fmas_f32 v57, v57, v61, v64
	v_div_fixup_f32 v57, v57, v30, 1.0
	v_lshlrev_b32_e32 v30, 16, v40
	v_sub_f32_e32 v56, v30, v56
	v_lshlrev_b32_e32 v61, 16, v50
	v_add_f32_e32 v55, v55, v56
	v_and_b32_e32 v40, 0xffff0000, v40
	v_fma_f32 v56, v31, v55, -v30
	v_sub_f32_e32 v63, v61, v30
	v_sub_f32_e32 v30, v40, v58
	v_lshlrev_b32_e32 v58, 16, v39
	v_and_b32_e32 v39, 0xffff0000, v39
	v_sub_f32_e32 v59, v58, v59
	v_sub_f32_e32 v62, v39, v62
	v_add_f32_e32 v34, v34, v30
	v_add_f32_e32 v59, v60, v59
	v_add_f32_e32 v35, v35, v62
	v_fma_f32 v30, v31, v34, -v40
	v_fma_f32 v60, v31, v59, -v58
	v_fma_f32 v31, v31, v35, -v39
	v_cvt_pk_bf16_f32 v30, v56, v30
	v_lshlrev_b32_e32 v56, 16, v43
	v_and_b32_e32 v43, 0xffff0000, v43
	v_cvt_pk_bf16_f32 v31, v60, v31
	global_store_dwordx2 v[32:33], v[30:31], off offset:1536
	v_sub_f32_e32 v31, v43, v39
	v_max_i32_e32 v30, 1, v48
	v_min_i32_e32 v39, 0x3fff, v48
	v_sub_u32_e32 v30, v39, v30
	v_add_u32_e32 v30, 2, v30
	v_cvt_f32_i32_e32 v30, v30
	v_and_b32_e32 v50, 0xffff0000, v50
	v_sub_f32_e32 v40, v50, v40
	v_sub_f32_e32 v58, v56, v58
	v_div_scale_f32 v39, s[2:3], v30, v30, 1.0
	v_rcp_f32_e32 v60, v39
	s_nop 0
	v_fma_f32 v62, -v39, v60, 1.0
	v_fmac_f32_e32 v60, v62, v60
	v_div_scale_f32 v62, vcc, 1.0, v30, 1.0
	v_mul_f32_e32 v64, v62, v60
	v_fma_f32 v66, -v39, v64, v62
	v_fmac_f32_e32 v64, v66, v60
	v_fma_f32 v39, -v39, v64, v62
	v_div_fmas_f32 v39, v39, v60, v64
	v_div_fixup_f32 v39, v39, v30, 1.0
	v_lshlrev_b32_e32 v30, 16, v42
	v_sub_f32_e32 v62, v30, v65
	v_lshlrev_b32_e32 v60, 16, v52
	v_add_f32_e32 v55, v55, v62
	v_fma_f32 v62, v57, v55, -v30
	v_add_f32_e32 v55, v55, v63
	v_sub_f32_e32 v30, v60, v30
	v_and_b32_e32 v42, 0xffff0000, v42
	v_fma_f32 v63, v39, v55, -v61
	v_add_f32_e32 v55, v55, v30
	v_sub_f32_e32 v30, v42, v38
	v_add_f32_e32 v30, v34, v30
	v_and_b32_e32 v52, 0xffff0000, v52
	v_fma_f32 v34, v57, v30, -v42
	v_add_f32_e32 v38, v30, v40
	v_cvt_pk_bf16_f32 v30, v62, v34
	v_sub_f32_e32 v34, v52, v42
	v_lshlrev_b32_e32 v42, 16, v41
	v_sub_f32_e32 v36, v42, v36
	v_and_b32_e32 v41, 0xffff0000, v41
	v_fma_f32 v40, v39, v38, -v50
	v_add_f32_e32 v34, v38, v34
	v_lshlrev_b32_e32 v38, 16, v51
	v_add_f32_e32 v36, v59, v36
	v_sub_f32_e32 v37, v41, v37
	v_fma_f32 v59, v57, v36, -v42
	v_add_f32_e32 v36, v36, v58
	v_sub_f32_e32 v42, v38, v42
	v_add_f32_e32 v35, v35, v37
	v_fma_f32 v58, v39, v36, -v56
	v_add_f32_e32 v36, v36, v42
	v_and_b32_e32 v42, 0xffff0000, v51
	v_fma_f32 v37, v57, v35, -v41
	v_add_f32_e32 v35, v35, v31
	v_cvt_pk_bf16_f32 v31, v59, v37
	global_store_dwordx2 v[32:33], v[30:31], off offset:2048
	v_cvt_pk_bf16_f32 v30, v63, v40
	v_fma_f32 v39, v39, v35, -v43
	v_cvt_pk_bf16_f32 v31, v58, v39
	global_store_dwordx2 v[32:33], v[30:31], off offset:2560
	v_sub_f32_e32 v30, v42, v41
	v_add_f32_e32 v35, v35, v30
	v_max_i32_e32 v30, 1, v49
	v_min_i32_e32 v31, 0x3fff, v49
	v_sub_u32_e32 v30, v31, v30
	v_add_u32_e32 v30, 2, v30
	v_cvt_f32_i32_e32 v30, v30
	v_div_scale_f32 v31, s[2:3], v30, v30, 1.0
	v_rcp_f32_e32 v37, v31
	s_nop 0
; __device__ __forceinline__ unsigned pk2(float lo, float hi) { unsigned r; asm("v_cvt_pk_bf16_f32 %0, %1, %2" : "=v"(r) : "v"(lo), "v"(hi)); return r; }
; __device__ __forceinline__ float bflo(unsigned u) { return __uint_as_float(u << 16); }
; __device__ __forceinline__ float bfhi(unsigned u) { return __uint_as_float(u & 0xFFFF0000u); }
; template <int J> __device__ __forceinline__ void pool_group(const bf16_t* hbuf, bf16_t* pl, int c0, int lane) {
;     ...
;     for (int k = 0; k < NR; ++k) { const int tt = c0 - H + k; const bool ok = tt >= 0 && tt < SEQ; const int tc = ok ? tt : c0;
;         raw[k] = *((const u32x2*)(hbuf + (size_t)tc * D + 256 * J) + lane); if (!ok) raw[k] = (u32x2){0u, 0u}; }
;     float s0 = 0.f, s1 = 0.f, s2 = 0.f, s3 = 0.f;
; #pragma unroll
;     for (int k = 0; k < W; ++k) { s0 += bflo(raw[k].x); s1 += bfhi(raw[k].x); s2 += bflo(raw[k].y); s3 += bfhi(raw[k].y); }
; #pragma unroll
;     for (int i = 0; i < 8; ++i) {
;         const int t = c0 + i; int lo = t - H, hi = t + H - 1; lo = lo < 0 ? 0 : lo; hi = hi > SEQ - 1 ? SEQ - 1 : hi;
;         const float ic = 1.f / (float)(hi - lo + 1);
;         const u32x2 self = raw[i + H];
;         u32x2 o; o.x = pk2(s0 * ic - bflo(self.x), s1 * ic - bfhi(self.x)); o.y = pk2(s2 * ic - bflo(self.y), s3 * ic - bfhi(self.y));
;         *((u32x2*)(pl + ((size_t)J * SEQ + t) * 256) + lane) = o;
;         if (i < 7) { s0 += bflo(raw[i + W].x) - bflo(raw[i].x); s1 += bfhi(raw[i + W].x) - bfhi(raw[i].x); s2 += bflo(raw[i + W].y) - bflo(raw[i].y); s3 += bfhi(raw[i + W].y) - bfhi(raw[i].y); }
	v_fma_f32 v39, -v31, v37, 1.0
	v_fmac_f32_e32 v37, v39, v37
	v_div_scale_f32 v39, vcc, 1.0, v30, 1.0
	v_mul_f32_e32 v40, v39, v37
	v_fma_f32 v41, -v31, v40, v39
	v_fmac_f32_e32 v40, v41, v37
	v_fma_f32 v31, -v31, v40, v39
	v_div_fmas_f32 v31, v31, v37, v40
	v_max_i32_e32 v40, 1, v3
	v_min_i32_e32 v41, 0x3fff, v3
	v_sub_u32_e32 v40, v41, v40
	v_add_u32_e32 v40, 2, v40
	v_cvt_f32_i32_e32 v40, v40
	v_div_fixup_f32 v31, v31, v30, 1.0
	v_fma_f32 v30, v31, v55, -v60
	v_fma_f32 v37, v31, v34, -v52
	v_div_scale_f32 v41, s[2:3], v40, v40, 1.0
	v_cvt_pk_bf16_f32 v30, v30, v37
	v_fma_f32 v37, v31, v36, -v38
	v_fma_f32 v31, v31, v35, -v42
	v_rcp_f32_e32 v42, v41
	v_cvt_pk_bf16_f32 v31, v37, v31
	global_store_dwordx2 v[32:33], v[30:31], off offset:3072
	v_and_b32_e32 v31, 0xffff0000, v54
	v_sub_f32_e32 v30, v31, v43
	v_lshlrev_b32_e32 v37, 16, v54
	v_add_f32_e32 v35, v35, v30
	v_sub_f32_e32 v30, v37, v56
	v_fma_f32 v43, -v41, v42, 1.0
	v_add_f32_e32 v36, v36, v30
	v_and_b32_e32 v30, 0xffff0000, v53
	v_fmac_f32_e32 v42, v43, v42
	v_div_scale_f32 v43, vcc, 1.0, v40, 1.0
	v_sub_f32_e32 v38, v30, v50
	v_mul_f32_e32 v50, v43, v42
	v_fma_f32 v51, -v41, v50, v43
	v_fmac_f32_e32 v50, v51, v42
	v_fma_f32 v41, -v41, v50, v43
	v_add_f32_e32 v34, v34, v38
	v_lshlrev_b32_e32 v38, 16, v53
	v_div_fmas_f32 v41, v41, v42, v50
	v_sub_f32_e32 v39, v38, v61
	v_div_fixup_f32 v40, v41, v40, 1.0
	v_add_f32_e32 v39, v55, v39
	v_fma_f32 v30, v40, v34, -v30
	v_fma_f32 v38, v40, v39, -v38
	v_cvt_pk_bf16_f32 v30, v38, v30
	v_fma_f32 v31, v40, v35, -v31
	v_fma_f32 v34, v40, v36, -v37
	v_cvt_pk_bf16_f32 v31, v34, v31
	global_store_dwordx2 v[32:33], v[30:31], off offset:3584
	global_load_dwordx2 v[120:121], v[12:13], off offset:512
	global_load_dwordx2 v[122:123], v[14:15], off offset:512
	global_load_dwordx2 v[124:125], v[16:17], off offset:512
	global_load_dwordx2 v[126:127], v[18:19], off offset:512
	global_load_dwordx2 v[128:129], v[20:21], off offset:512
	global_load_dwordx2 v[130:131], v[22:23], off offset:512
	global_load_dwordx2 v[132:133], v[24:25], off offset:512
	global_load_dwordx2 v[134:135], v[26:27], off offset:512
	global_load_dwordx2 v[136:137], v[28:29], off offset:512
	v_add_u32_e32 v30, -2, v2
	v_cmp_gt_u32_e64 s[6:7], s33, v30
	v_div_scale_f32 v71, vcc, 1.0, v68, 1.0
	s_nop 0
	v_cndmask_b32_e64 v30, v2, v30, s[6:7]
	v_ashrrev_i32_e32 v31, 31, v30
	v_lshlrev_b64 v[30:31], 11, v[30:31]
	v_lshl_add_u64 v[30:31], v[4:5], 0, v[30:31]
	global_load_dwordx2 v[32:33], v[30:31], off offset:512
	v_mul_f32_e32 v72, v71, v70
	v_fma_f32 v73, -v69, v72, v71
	v_fmac_f32_e32 v72, v73, v70
	v_max_i32_e32 v73, 2, v45
	v_sub_u32_e32 v73, v74, v73
	v_add_u32_e32 v73, 4, v73
	v_cvt_f32_i32_e32 v73, v73
	v_fma_f32 v69, -v69, v72, v71
	v_div_fmas_f32 v69, v69, v70, v72
	v_div_fixup_f32 v68, v69, v68, 1.0
	v_div_scale_f32 v74, s[2:3], v73, v73, 1.0
	v_rcp_f32_e32 v75, v74
	s_waitcnt vmcnt(0)
	v_cndmask_b32_e64 v42, 0, v33, s[6:7]
	v_cndmask_b32_e64 v43, 0, v32, s[6:7]
	s_waitcnt vmcnt(0)
	v_mov_b64_e32 v[32:33], v[120:121]
	v_fma_f32 v76, -v74, v75, 1.0
	v_fmac_f32_e32 v75, v76, v75
	v_div_scale_f32 v76, vcc, 1.0, v73, 1.0
	v_mul_f32_e32 v77, v76, v75
	v_fma_f32 v78, -v74, v77, v76
	v_fmac_f32_e32 v77, v78, v75
	v_max_i32_e32 v78, 2, v44
	v_sub_u32_e32 v78, v79, v78
	v_add_u32_e32 v78, 4, v78
	v_cvt_f32_i32_e32 v78, v78
	v_fma_f32 v74, -v74, v77, v76
	v_div_fmas_f32 v74, v74, v75, v77
	v_div_fixup_f32 v73, v74, v73, 1.0
	v_div_scale_f32 v79, s[2:3], v78, v78, 1.0
	v_rcp_f32_e32 v80, v79
	v_lshlrev_b32_e32 v65, 16, v42
	v_add_f32_e32 v66, 0, v65
	v_and_b32_e32 v42, 0xffff0000, v42
	v_fma_f32 v81, -v79, v80, 1.0
	v_fmac_f32_e32 v80, v81, v80
	v_div_scale_f32 v81, vcc, 1.0, v78, 1.0
	v_mul_f32_e32 v82, v81, v80
	v_fma_f32 v83, -v79, v82, v81
	v_fmac_f32_e32 v82, v83, v80
	v_fma_f32 v79, -v79, v82, v81
	v_div_fmas_f32 v79, v79, v80, v82
	v_div_fixup_f32 v78, v79, v78, 1.0
	v_add_f32_e32 v67, 0, v42
	s_mov_b32 s2, 0x4efb9000
	s_waitcnt vmcnt(0)
	v_cndmask_b32_e64 v50, 0, v33, s[16:17]
	v_cndmask_b32_e64 v51, 0, v32, s[16:17]
	s_waitcnt vmcnt(0)
	v_mov_b64_e32 v[32:33], v[122:123]
	v_lshlrev_b32_e32 v74, 16, v51
	v_and_b32_e32 v51, 0xffff0000, v51
	v_lshlrev_b32_e32 v77, 16, v50
	v_add_f32_e32 v66, v66, v77
	v_and_b32_e32 v50, 0xffff0000, v50
	v_add_f32_e32 v67, v67, v50
	s_waitcnt vmcnt(0)
	v_cndmask_b32_e64 v52, 0, v33, s[0:1]
	v_cndmask_b32_e64 v53, 0, v32, s[0:1]
	s_waitcnt vmcnt(0)
	v_mov_b64_e32 v[32:33], v[124:125]
	v_lshlrev_b32_e32 v79, 16, v53
	s_waitcnt vmcnt(0)
	v_cndmask_b32_e64 v54, 0, v33, s[0:1]
	v_cndmask_b32_e64 v55, 0, v32, s[0:1]
	s_waitcnt vmcnt(0)
	v_mov_b64_e32 v[32:33], v[126:127]
	v_lshlrev_b32_e32 v70, 16, v55
	v_and_b32_e32 v55, 0xffff0000, v55
	v_lshlrev_b32_e32 v71, 16, v54
	v_and_b32_e32 v54, 0xffff0000, v54
	s_waitcnt vmcnt(0)
	v_cndmask_b32_e64 v56, 0, v33, s[0:1]
	v_cndmask_b32_e64 v57, 0, v32, s[0:1]
	s_waitcnt vmcnt(0)
	v_mov_b64_e32 v[32:33], v[128:129]
	v_lshlrev_b32_e32 v69, 16, v57
	v_and_b32_e32 v57, 0xffff0000, v57
	v_lshlrev_b32_e32 v72, 16, v56
	v_sub_f32_e32 v65, v72, v65
	v_and_b32_e32 v56, 0xffff0000, v56
	v_sub_f32_e32 v42, v56, v42
	s_waitcnt vmcnt(0)
	v_cndmask_b32_e64 v58, 0, v33, s[0:1]
	v_cndmask_b32_e64 v59, 0, v32, s[0:1]
	s_waitcnt vmcnt(0)
	v_mov_b64_e32 v[32:33], v[130:131]
	v_lshlrev_b32_e32 v75, 16, v59
	v_and_b32_e32 v59, 0xffff0000, v59
	v_lshlrev_b32_e32 v76, 16, v58
	v_sub_f32_e32 v77, v76, v77
	v_and_b32_e32 v58, 0xffff0000, v58
	s_waitcnt vmcnt(0)
	v_cndmask_b32_e64 v60, 0, v33, s[0:1]
	v_cndmask_b32_e64 v61, 0, v32, s[0:1]
	s_waitcnt vmcnt(0)
	v_mov_b64_e32 v[32:33], v[132:133]
	v_lshlrev_b32_e32 v80, 16, v61
	s_waitcnt vmcnt(0)
; __device__ __forceinline__ unsigned pk2(float lo, float hi) { unsigned r; asm("v_cvt_pk_bf16_f32 %0, %1, %2" : "=v"(r) : "v"(lo), "v"(hi)); return r; }
; __device__ __forceinline__ float bflo(unsigned u) { return __uint_as_float(u << 16); }
; __device__ __forceinline__ float bfhi(unsigned u) { return __uint_as_float(u & 0xFFFF0000u); }
; template <int J> __device__ __forceinline__ void pool_group(const bf16_t* hbuf, bf16_t* pl, int c0, int lane) {
;     ...
;     for (int k = 0; k < NR; ++k) { const int tt = c0 - H + k; const bool ok = tt >= 0 && tt < SEQ; const int tc = ok ? tt : c0;
;         raw[k] = *((const u32x2*)(hbuf + (size_t)tc * D + 256 * J) + lane); if (!ok) raw[k] = (u32x2){0u, 0u}; }
;     float s0 = 0.f, s1 = 0.f, s2 = 0.f, s3 = 0.f;
; #pragma unroll
;     for (int k = 0; k < W; ++k) { s0 += bflo(raw[k].x); s1 += bfhi(raw[k].x); s2 += bflo(raw[k].y); s3 += bfhi(raw[k].y); }
; #pragma unroll
;     for (int i = 0; i < 8; ++i) {
;         const int t = c0 + i; int lo = t - H, hi = t + H - 1; lo = lo < 0 ? 0 : lo; hi = hi > SEQ - 1 ? SEQ - 1 : hi;
;         const float ic = 1.f / (float)(hi - lo + 1);
;         const u32x2 self = raw[i + H];
;         u32x2 o; o.x = pk2(s0 * ic - bflo(self.x), s1 * ic - bfhi(self.x)); o.y = pk2(s2 * ic - bflo(self.y), s3 * ic - bfhi(self.y));
;         *((u32x2*)(pl + ((size_t)J * SEQ + t) * 256) + lane) = o;
;         if (i < 7) { s0 += bflo(raw[i + W].x) - bflo(raw[i].x); s1 += bfhi(raw[i + W].x) - bfhi(raw[i].x); s2 += bflo(raw[i + W].y) - bflo(raw[i].y); s3 += bfhi(raw[i + W].y) - bfhi(raw[i].y); }
	v_cndmask_b32_e64 v38, 0, v33, s[0:1]
	v_cndmask_b32_e64 v39, 0, v32, s[0:1]
	s_waitcnt vmcnt(0)
	v_mov_b64_e32 v[32:33], v[134:135]
	s_waitcnt vmcnt(0)
	v_cndmask_b32_e64 v36, 0, v33, s[0:1]
	v_cndmask_b32_e64 v37, 0, v32, s[0:1]
	s_waitcnt vmcnt(0)
	v_mov_b64_e32 v[32:33], v[136:137]
	s_waitcnt vmcnt(0)
	v_cndmask_b32_e64 v35, 0, v32, s[0:1]
	v_add_u32_e32 v32, 8, v2
	v_cmp_gt_u32_e64 s[4:5], s33, v32
	v_cndmask_b32_e64 v34, 0, v33, s[0:1]
	s_nop 0
	v_cndmask_b32_e64 v32, v2, v32, s[4:5]
	v_ashrrev_i32_e32 v33, 31, v32
	v_lshlrev_b64 v[32:33], 11, v[32:33]
	v_lshl_add_u64 v[32:33], v[4:5], 0, v[32:33]
	global_load_dwordx2 v[40:41], v[32:33], off offset:512
	s_waitcnt vmcnt(0)
	v_cndmask_b32_e64 v62, 0, v40, s[4:5]
	v_lshlrev_b32_e32 v40, 16, v43
	v_cndmask_b32_e64 v63, 0, v41, s[4:5]
	v_add_f32_e32 v41, 0, v40
	v_add_f32_e32 v41, v41, v74
	v_add_f32_e32 v41, v41, v79
	v_add_f32_e32 v41, v41, v70
	v_sub_f32_e32 v40, v69, v40
	v_and_b32_e32 v43, 0xffff0000, v43
	v_fma_f32 v81, v68, v41, -v79
	v_add_f32_e32 v40, v41, v40
	v_sub_f32_e32 v41, v75, v74
	v_add_f32_e32 v64, 0, v43
	v_fma_f32 v82, v73, v40, -v70
	v_add_f32_e32 v40, v40, v41
	v_sub_f32_e32 v41, v80, v79
	v_add_f32_e32 v64, v64, v51
	v_add_f32_e32 v79, v40, v41
	v_and_b32_e32 v41, 0xffff0000, v53
	v_fma_f32 v74, v78, v40, -v69
	v_add_f32_e32 v40, v64, v41
	v_add_f32_e32 v40, v40, v55
	v_sub_f32_e32 v43, v57, v43
	v_and_b32_e32 v53, 0xffff0000, v61
	v_fma_f32 v61, v68, v40, -v41
	v_add_f32_e32 v40, v40, v43
	v_sub_f32_e32 v43, v59, v51
	v_add_f32_e32 v43, v40, v43
	v_sub_f32_e32 v41, v53, v41
	v_fma_f32 v64, v73, v40, -v55
	v_cvt_pk_bf16_f32 v40, v81, v61
	v_add_f32_e32 v61, v43, v41
	v_lshlrev_b32_e32 v41, 16, v52
	v_fma_f32 v51, v78, v43, -v57
	v_add_f32_e32 v43, v66, v41
	v_add_f32_e32 v43, v43, v71
	v_lshlrev_b32_e32 v81, 16, v60
	v_fma_f32 v66, v68, v43, -v41
	v_add_f32_e32 v43, v43, v65
	v_fma_f32 v65, v73, v43, -v71
	v_add_f32_e32 v43, v43, v77
	v_sub_f32_e32 v41, v81, v41
	v_and_b32_e32 v52, 0xffff0000, v52
	v_add_f32_e32 v83, v43, v41
	v_add_f32_e32 v41, v67, v52
	v_add_f32_e32 v41, v41, v54
	v_fma_f32 v77, v78, v43, -v72
	v_fma_f32 v43, v68, v41, -v52
	v_add_f32_e32 v41, v41, v42
	v_sub_f32_e32 v42, v58, v50
	v_add_f32_e32 v50, v41, v42
	v_add_co_u32_e32 v42, vcc, s2, v10
	v_fma_f32 v67, v73, v41, -v54
	v_cvt_pk_bf16_f32 v41, v66, v43
	s_nop 0
	v_addc_co_u32_e32 v43, vcc, 0, v11, vcc
	global_store_dwordx2 v[42:43], v[40:41], off
	v_cvt_pk_bf16_f32 v40, v82, v64
	v_and_b32_e32 v60, 0xffff0000, v60
	v_cvt_pk_bf16_f32 v41, v65, v67
	global_store_dwordx2 v[42:43], v[40:41], off offset:512
	v_cvt_pk_bf16_f32 v40, v74, v51
	v_fma_f32 v68, v78, v50, -v56
	v_cvt_pk_bf16_f32 v41, v77, v68
	global_store_dwordx2 v[42:43], v[40:41], off offset:1024
	v_sub_f32_e32 v40, v60, v52
	v_add_f32_e32 v50, v50, v40
	v_max_i32_e32 v40, 2, v46
	v_min_i32_e32 v41, 0x3ffe, v46
	v_sub_u32_e32 v40, v41, v40
	v_add_u32_e32 v40, 4, v40
	v_cvt_f32_i32_e32 v40, v40
	v_div_scale_f32 v85, s[2:3], v84, v84, 1.0
	v_rcp_f32_e32 v86, v85
	v_div_scale_f32 v41, s[2:3], v40, v40, 1.0
	v_rcp_f32_e32 v51, v41
	v_fma_f32 v87, -v85, v86, 1.0
	v_fmac_f32_e32 v86, v87, v86
	v_fma_f32 v52, -v41, v51, 1.0
	v_fmac_f32_e32 v51, v52, v51
	v_div_scale_f32 v52, vcc, 1.0, v40, 1.0
	v_mul_f32_e32 v64, v52, v51
	v_fma_f32 v65, -v41, v64, v52
	v_fmac_f32_e32 v64, v65, v51
	v_fma_f32 v41, -v41, v64, v52
	v_div_fmas_f32 v41, v41, v51, v64
	v_div_fixup_f32 v41, v41, v40, 1.0
	v_fma_f32 v40, v41, v79, -v75
	v_fma_f32 v51, v41, v61, -v59
	v_cvt_pk_bf16_f32 v40, v40, v51
	v_fma_f32 v51, v41, v83, -v76
	v_fma_f32 v41, v41, v50, -v58
	v_cvt_pk_bf16_f32 v41, v51, v41
	v_and_b32_e32 v51, 0xffff0000, v39
	global_store_dwordx2 v[42:43], v[40:41], off offset:1536
	v_lshlrev_b32_e32 v40, 16, v39
	v_sub_f32_e32 v39, v51, v55
	v_lshlrev_b32_e32 v55, 16, v38
	v_and_b32_e32 v64, 0xffff0000, v38
	v_add_f32_e32 v52, v61, v39
	v_sub_f32_e32 v39, v55, v71
	v_sub_f32_e32 v38, v64, v54
	v_add_f32_e32 v61, v83, v39
	v_add_f32_e32 v50, v50, v38
	v_max_i32_e32 v38, 2, v47
	v_min_i32_e32 v39, 0x3ffe, v47
	v_sub_u32_e32 v38, v39, v38
	v_add_u32_e32 v38, 4, v38
	v_cvt_f32_i32_e32 v38, v38
	v_sub_f32_e32 v41, v40, v70
	v_add_f32_e32 v41, v79, v41
	v_div_scale_f32 v39, s[2:3], v38, v38, 1.0
	v_rcp_f32_e32 v54, v39
	s_nop 0
	v_fma_f32 v65, -v39, v54, 1.0
	v_fmac_f32_e32 v54, v65, v54
	v_div_scale_f32 v65, vcc, 1.0, v38, 1.0
	v_mul_f32_e32 v66, v65, v54
	v_fma_f32 v67, -v39, v66, v65
	v_fmac_f32_e32 v66, v67, v54
	v_fma_f32 v39, -v39, v66, v65
	v_div_fmas_f32 v39, v39, v54, v66
	v_div_fixup_f32 v39, v39, v38, 1.0
	v_fma_f32 v38, v39, v41, -v80
	v_fma_f32 v54, v39, v52, -v53
	v_cvt_pk_bf16_f32 v38, v38, v54
	v_fma_f32 v54, v39, v61, -v81
	v_fma_f32 v39, v39, v50, -v60
	v_cvt_pk_bf16_f32 v39, v54, v39
	global_store_dwordx2 v[42:43], v[38:39], off offset:2048
	v_lshlrev_b32_e32 v38, 16, v37
	v_sub_f32_e32 v39, v38, v69
	v_add_f32_e32 v39, v41, v39
	v_and_b32_e32 v41, 0xffff0000, v37
	v_sub_f32_e32 v37, v41, v57
	v_lshlrev_b32_e32 v54, 16, v36
	v_add_f32_e32 v52, v52, v37
	v_sub_f32_e32 v37, v54, v72
	v_add_f32_e32 v57, v61, v37
	v_and_b32_e32 v61, 0xffff0000, v36
	v_sub_f32_e32 v36, v61, v56
	v_add_f32_e32 v50, v50, v36
	v_max_i32_e32 v36, 2, v48
	v_min_i32_e32 v37, 0x3ffe, v48
	v_sub_u32_e32 v36, v37, v36
	v_add_u32_e32 v36, 4, v36
	v_cvt_f32_i32_e32 v36, v36
	v_div_scale_f32 v37, s[2:3], v36, v36, 1.0
	v_rcp_f32_e32 v56, v37
	s_nop 0
	v_fma_f32 v65, -v37, v56, 1.0
	v_fmac_f32_e32 v56, v65, v56
	v_div_scale_f32 v65, vcc, 1.0, v36, 1.0
	v_mul_f32_e32 v66, v65, v56
	v_fma_f32 v67, -v37, v66, v65
	v_fmac_f32_e32 v66, v67, v56
	v_fma_f32 v37, -v37, v66, v65
; __device__ __forceinline__ unsigned pk2(float lo, float hi) { unsigned r; asm("v_cvt_pk_bf16_f32 %0, %1, %2" : "=v"(r) : "v"(lo), "v"(hi)); return r; }
; __device__ __forceinline__ float bflo(unsigned u) { return __uint_as_float(u << 16); }
; __device__ __forceinline__ float bfhi(unsigned u) { return __uint_as_float(u & 0xFFFF0000u); }
; template <int J> __device__ __forceinline__ void pool_group(const bf16_t* hbuf, bf16_t* pl, int c0, int lane) {
;     ...
;     for (int k = 0; k < NR; ++k) { const int tt = c0 - H + k; const bool ok = tt >= 0 && tt < SEQ; const int tc = ok ? tt : c0;
;         raw[k] = *((const u32x2*)(hbuf + (size_t)tc * D + 256 * J) + lane); if (!ok) raw[k] = (u32x2){0u, 0u}; }
;     float s0 = 0.f, s1 = 0.f, s2 = 0.f, s3 = 0.f;
; #pragma unroll
;     for (int k = 0; k < W; ++k) { s0 += bflo(raw[k].x); s1 += bfhi(raw[k].x); s2 += bflo(raw[k].y); s3 += bfhi(raw[k].y); }
; #pragma unroll
;     for (int i = 0; i < 8; ++i) {
;         const int t = c0 + i; int lo = t - H, hi = t + H - 1; lo = lo < 0 ? 0 : lo; hi = hi > SEQ - 1 ? SEQ - 1 : hi;
;         const float ic = 1.f / (float)(hi - lo + 1);
;         const u32x2 self = raw[i + H];
;         u32x2 o; o.x = pk2(s0 * ic - bflo(self.x), s1 * ic - bfhi(self.x)); o.y = pk2(s2 * ic - bflo(self.y), s3 * ic - bfhi(self.y));
;         *((u32x2*)(pl + ((size_t)J * SEQ + t) * 256) + lane) = o;
;         if (i < 7) { s0 += bflo(raw[i + W].x) - bflo(raw[i].x); s1 += bfhi(raw[i + W].x) - bfhi(raw[i].x); s2 += bflo(raw[i + W].y) - bflo(raw[i].y); s3 += bfhi(raw[i + W].y) - bfhi(raw[i].y); }
	v_div_fmas_f32 v37, v37, v56, v66
	v_div_fixup_f32 v37, v37, v36, 1.0
	v_fma_f32 v36, v37, v39, -v40
	v_fma_f32 v40, v37, v52, -v51
	v_cvt_pk_bf16_f32 v36, v36, v40
	v_fma_f32 v40, v37, v57, -v55
	v_fma_f32 v37, v37, v50, -v64
	v_cvt_pk_bf16_f32 v37, v40, v37
	global_store_dwordx2 v[42:43], v[36:37], off offset:2560
	v_lshlrev_b32_e32 v36, 16, v35
	v_sub_f32_e32 v37, v36, v75
	v_add_f32_e32 v37, v39, v37
	v_and_b32_e32 v39, 0xffff0000, v35
	v_sub_f32_e32 v35, v39, v59
	v_lshlrev_b32_e32 v51, 16, v34
	v_and_b32_e32 v55, 0xffff0000, v34
	v_add_f32_e32 v40, v52, v35
	v_sub_f32_e32 v35, v51, v76
	v_sub_f32_e32 v34, v55, v58
	v_add_f32_e32 v52, v57, v35
	v_add_f32_e32 v50, v50, v34
	v_max_i32_e32 v34, 2, v49
	v_min_i32_e32 v35, 0x3ffe, v49
	v_sub_u32_e32 v34, v35, v34
	v_add_u32_e32 v34, 4, v34
	v_cvt_f32_i32_e32 v34, v34
	v_div_scale_f32 v35, s[2:3], v34, v34, 1.0
	v_rcp_f32_e32 v56, v35
	s_nop 0
	v_fma_f32 v57, -v35, v56, 1.0
	v_fmac_f32_e32 v56, v57, v56
	v_div_scale_f32 v57, vcc, 1.0, v34, 1.0
	v_mul_f32_e32 v58, v57, v56
	v_fma_f32 v59, -v35, v58, v57
	v_fmac_f32_e32 v58, v59, v56
	v_fma_f32 v35, -v35, v58, v57
	v_div_fmas_f32 v35, v35, v56, v58
	v_div_fixup_f32 v35, v35, v34, 1.0
	v_fma_f32 v34, v35, v37, -v38
	v_fma_f32 v38, v35, v40, -v41
	v_cvt_pk_bf16_f32 v34, v34, v38
	v_fma_f32 v38, v35, v52, -v54
	v_fma_f32 v35, v35, v50, -v61
	v_cvt_pk_bf16_f32 v35, v38, v35
	global_store_dwordx2 v[42:43], v[34:35], off offset:3072
	v_and_b32_e32 v34, 0xffff0000, v63
	v_sub_f32_e32 v34, v34, v60
	v_add_f32_e32 v35, v50, v34
	v_lshlrev_b32_e32 v34, 16, v63
	v_sub_f32_e32 v34, v34, v81
	v_add_f32_e32 v38, v52, v34
	v_and_b32_e32 v34, 0xffff0000, v62
	v_sub_f32_e32 v34, v34, v53
	v_add_f32_e32 v34, v40, v34
	v_lshlrev_b32_e32 v40, 16, v62
	v_sub_f32_e32 v40, v40, v80
	v_add_f32_e32 v37, v37, v40
	v_max_i32_e32 v40, 2, v3
	v_min_i32_e32 v41, 0x3ffe, v3
	v_sub_u32_e32 v40, v41, v40
	v_add_u32_e32 v40, 4, v40
	v_cvt_f32_i32_e32 v40, v40
	v_div_scale_f32 v41, s[2:3], v40, v40, 1.0
	v_rcp_f32_e32 v50, v41
	s_nop 0
	v_fma_f32 v52, -v41, v50, 1.0
	v_fmac_f32_e32 v50, v52, v50
	v_div_scale_f32 v52, vcc, 1.0, v40, 1.0
	v_mul_f32_e32 v53, v52, v50
	v_fma_f32 v54, -v41, v53, v52
	v_fmac_f32_e32 v53, v54, v50
	v_fma_f32 v41, -v41, v53, v52
	v_div_fmas_f32 v41, v41, v50, v53
	v_div_fixup_f32 v40, v41, v40, 1.0
	v_fma_f32 v34, v40, v34, -v39
	v_fma_f32 v36, v40, v37, -v36
	v_cvt_pk_bf16_f32 v34, v36, v34
	v_fma_f32 v35, v40, v35, -v55
	v_fma_f32 v36, v40, v38, -v51
	v_cvt_pk_bf16_f32 v35, v36, v35
	global_store_dwordx2 v[42:43], v[34:35], off offset:3584
	global_load_dwordx2 v[120:121], v[30:31], off offset:1024
	global_load_dwordx2 v[122:123], v[12:13], off offset:1024
	global_load_dwordx2 v[124:125], v[14:15], off offset:1024
	global_load_dwordx2 v[126:127], v[16:17], off offset:1024
	global_load_dwordx2 v[128:129], v[18:19], off offset:1024
	global_load_dwordx2 v[130:131], v[20:21], off offset:1024
	global_load_dwordx2 v[132:133], v[22:23], off offset:1024
	global_load_dwordx2 v[134:135], v[24:25], off offset:1024
	global_load_dwordx2 v[136:137], v[26:27], off offset:1024
	global_load_dwordx2 v[138:139], v[28:29], off offset:1024
	global_load_dwordx2 v[140:141], v[32:33], off offset:1024
	v_add_u32_e32 v34, -4, v2
	v_cmp_gt_u32_e64 s[8:9], s33, v34
	v_div_scale_f32 v87, vcc, 1.0, v84, 1.0
	s_nop 0
	v_cndmask_b32_e64 v34, v2, v34, s[8:9]
	v_ashrrev_i32_e32 v35, 31, v34
	v_lshlrev_b64 v[34:35], 11, v[34:35]
	v_lshl_add_u64 v[34:35], v[4:5], 0, v[34:35]
	global_load_dwordx2 v[36:37], v[34:35], off offset:1024
	v_mul_f32_e32 v88, v87, v86
	v_fma_f32 v89, -v85, v88, v87
	v_fmac_f32_e32 v88, v89, v86
	v_max_i32_e32 v89, 4, v45
	v_sub_u32_e32 v89, v90, v89
	v_add_u32_e32 v89, 8, v89
	v_cvt_f32_i32_e32 v89, v89
	v_fma_f32 v85, -v85, v88, v87
	v_div_fmas_f32 v85, v85, v86, v88
	v_div_fixup_f32 v84, v85, v84, 1.0
	v_div_scale_f32 v90, s[2:3], v89, v89, 1.0
	v_rcp_f32_e32 v91, v90
	s_waitcnt vmcnt(0)
	v_cndmask_b32_e64 v53, 0, v36, s[8:9]
	v_add_u32_e32 v36, -3, v2
	v_cmp_gt_u32_e64 s[10:11], s33, v36
	v_cndmask_b32_e64 v52, 0, v37, s[8:9]
	v_fma_f32 v92, -v90, v91, 1.0
	v_cndmask_b32_e64 v36, v2, v36, s[10:11]
	v_ashrrev_i32_e32 v37, 31, v36
	v_lshlrev_b64 v[36:37], 11, v[36:37]
	v_lshl_add_u64 v[36:37], v[4:5], 0, v[36:37]
	global_load_dwordx2 v[38:39], v[36:37], off offset:1024
	v_fmac_f32_e32 v91, v92, v91
	v_div_scale_f32 v92, vcc, 1.0, v89, 1.0
	v_mul_f32_e32 v93, v92, v91
	v_fma_f32 v94, -v90, v93, v92
	v_fmac_f32_e32 v93, v94, v91
	v_max_i32_e32 v94, 4, v44
	v_sub_u32_e32 v94, v95, v94
	v_add_u32_e32 v94, 8, v94
	v_cvt_f32_i32_e32 v94, v94
	v_fma_f32 v90, -v90, v93, v92
	v_div_fmas_f32 v90, v90, v91, v93
	v_lshlrev_b32_e32 v80, 16, v53
	v_div_scale_f32 v95, s[2:3], v94, v94, 1.0
	v_rcp_f32_e32 v96, v95
	v_and_b32_e32 v81, 0xffff0000, v53
	v_div_fixup_f32 v89, v90, v89, 1.0
	v_and_b32_e32 v83, 0xffff0000, v52
	v_fma_f32 v97, -v95, v96, 1.0
	v_fmac_f32_e32 v96, v97, v96
	v_div_scale_f32 v97, vcc, 1.0, v94, 1.0
	v_mul_f32_e32 v98, v97, v96
	v_fma_f32 v99, -v95, v98, v97
	v_fmac_f32_e32 v98, v99, v96
	v_fma_f32 v95, -v95, v98, v97
	v_div_fmas_f32 v95, v95, v96, v98
	v_div_fixup_f32 v94, v95, v94, 1.0
	v_lshlrev_b32_e32 v82, 16, v52
	v_add_f32_e32 v52, 0, v83
	v_add_f32_e32 v53, 0, v82
	s_waitcnt vmcnt(0)
	v_cndmask_b32_e64 v54, 0, v39, s[10:11]
	v_cndmask_b32_e64 v55, 0, v38, s[10:11]
	s_waitcnt vmcnt(0)
	v_mov_b64_e32 v[38:39], v[120:121]
	v_lshlrev_b32_e32 v90, 16, v55
	v_and_b32_e32 v55, 0xffff0000, v55
	v_lshlrev_b32_e32 v93, 16, v54
	v_and_b32_e32 v54, 0xffff0000, v54
	v_add_f32_e32 v52, v52, v54
	v_add_f32_e32 v53, v53, v93
	s_waitcnt vmcnt(0)
; __device__ __forceinline__ float bflo(unsigned u) { return __uint_as_float(u << 16); }
; __device__ __forceinline__ float bfhi(unsigned u) { return __uint_as_float(u & 0xFFFF0000u); }
; template <int J> __device__ __forceinline__ void pool_group(const bf16_t* hbuf, bf16_t* pl, int c0, int lane) {
;     ...
;     for (int k = 0; k < NR; ++k) { const int tt = c0 - H + k; const bool ok = tt >= 0 && tt < SEQ; const int tc = ok ? tt : c0;
;         raw[k] = *((const u32x2*)(hbuf + (size_t)tc * D + 256 * J) + lane); if (!ok) raw[k] = (u32x2){0u, 0u}; }
;     float s0 = 0.f, s1 = 0.f, s2 = 0.f, s3 = 0.f;
; #pragma unroll
;     for (int k = 0; k < W; ++k) { s0 += bflo(raw[k].x); s1 += bfhi(raw[k].x); s2 += bflo(raw[k].y); s3 += bfhi(raw[k].y); }
; #pragma unroll
;     for (int i = 0; i < 8; ++i) {
;         const int t = c0 + i; int lo = t - H, hi = t + H - 1; lo = lo < 0 ? 0 : lo; hi = hi > SEQ - 1 ? SEQ - 1 : hi;
;         const float ic = 1.f / (float)(hi - lo + 1);
	v_cndmask_b32_e64 v56, 0, v39, s[6:7]
	v_cndmask_b32_e64 v57, 0, v38, s[6:7]
	s_waitcnt vmcnt(0)
	v_mov_b64_e32 v[38:39], v[122:123]
	v_lshlrev_b32_e32 v95, 16, v57
	v_and_b32_e32 v57, 0xffff0000, v57
	v_lshlrev_b32_e32 v100, 16, v56
	v_and_b32_e32 v56, 0xffff0000, v56
	v_add_f32_e32 v101, v52, v56
	v_add_f32_e32 v53, v53, v100
	s_waitcnt vmcnt(0)
	v_cndmask_b32_e64 v58, 0, v39, s[16:17]
	v_cndmask_b32_e64 v59, 0, v38, s[16:17]
	s_waitcnt vmcnt(0)
	v_mov_b64_e32 v[38:39], v[124:125]
	s_waitcnt vmcnt(0)
	v_cndmask_b32_e64 v60, 0, v39, s[0:1]
	v_cndmask_b32_e64 v61, 0, v38, s[0:1]
	s_waitcnt vmcnt(0)
	v_mov_b64_e32 v[38:39], v[126:127]
	s_waitcnt vmcnt(0)
	v_cndmask_b32_e64 v62, 0, v39, s[0:1]
	v_cndmask_b32_e64 v63, 0, v38, s[0:1]
	s_waitcnt vmcnt(0)
	v_mov_b64_e32 v[38:39], v[128:129]
	s_waitcnt vmcnt(0)
	v_cndmask_b32_e64 v43, 0, v39, s[0:1]
	v_cndmask_b32_e64 v42, 0, v38, s[0:1]
	s_waitcnt vmcnt(0)
	v_mov_b64_e32 v[38:39], v[130:131]
	s_waitcnt vmcnt(0)
	v_cndmask_b32_e64 v64, 0, v39, s[0:1]
	v_cndmask_b32_e64 v65, 0, v38, s[0:1]
	s_waitcnt vmcnt(0)
	v_mov_b64_e32 v[38:39], v[132:133]
	v_lshlrev_b32_e32 v87, 16, v64
	v_and_b32_e32 v64, 0xffff0000, v64
	v_lshlrev_b32_e32 v86, 16, v65
	v_and_b32_e32 v65, 0xffff0000, v65
	s_waitcnt vmcnt(0)
	v_cndmask_b32_e64 v66, 0, v39, s[0:1]
	v_cndmask_b32_e64 v67, 0, v38, s[0:1]
	s_waitcnt vmcnt(0)
	v_mov_b64_e32 v[38:39], v[134:135]
	v_lshlrev_b32_e32 v88, 16, v66
	v_and_b32_e32 v66, 0xffff0000, v66
	v_sub_f32_e32 v83, v66, v83
	v_lshlrev_b32_e32 v85, 16, v67
	v_and_b32_e32 v67, 0xffff0000, v67
	s_waitcnt vmcnt(0)
	v_cndmask_b32_e64 v68, 0, v39, s[0:1]
	v_cndmask_b32_e64 v69, 0, v38, s[0:1]
	s_waitcnt vmcnt(0)
	v_mov_b64_e32 v[38:39], v[136:137]
	v_lshlrev_b32_e32 v92, 16, v68
	v_and_b32_e32 v68, 0xffff0000, v68
	v_sub_f32_e32 v54, v68, v54
	v_lshlrev_b32_e32 v91, 16, v69
	v_and_b32_e32 v69, 0xffff0000, v69
	s_waitcnt vmcnt(0)
	v_cndmask_b32_e64 v70, 0, v39, s[0:1]
	v_cndmask_b32_e64 v71, 0, v38, s[0:1]
	s_waitcnt vmcnt(0)
	v_mov_b64_e32 v[38:39], v[138:139]
	v_lshlrev_b32_e32 v99, 16, v70
	v_and_b32_e32 v70, 0xffff0000, v70
	v_sub_f32_e32 v56, v70, v56
	v_lshlrev_b32_e32 v96, 16, v71
	v_and_b32_e32 v71, 0xffff0000, v71
	s_waitcnt vmcnt(0)
	v_cndmask_b32_e64 v72, 0, v39, s[0:1]
	v_cndmask_b32_e64 v73, 0, v38, s[0:1]
	s_waitcnt vmcnt(0)
	v_mov_b64_e32 v[38:39], v[140:141]
	s_waitcnt vmcnt(0)
	v_cndmask_b32_e64 v75, 0, v38, s[4:5]
	v_add_u32_e32 v38, 9, v2
	v_cmp_gt_u32_e64 s[12:13], s33, v38
	v_cndmask_b32_e64 v74, 0, v39, s[4:5]
	s_nop 0
	v_cndmask_b32_e64 v38, v2, v38, s[12:13]
	v_ashrrev_i32_e32 v39, 31, v38
	v_lshlrev_b64 v[38:39], 11, v[38:39]
	v_lshl_add_u64 v[38:39], v[4:5], 0, v[38:39]
	global_load_dwordx2 v[40:41], v[38:39], off offset:1024
	s_waitcnt vmcnt(0)
	v_cndmask_b32_e64 v77, 0, v40, s[12:13]
	v_add_u32_e32 v40, 10, v2
	v_cmp_gt_u32_e64 s[14:15], s33, v40
	v_cndmask_b32_e64 v76, 0, v41, s[12:13]
	s_nop 0
	v_cndmask_b32_e64 v40, v2, v40, s[14:15]
	v_ashrrev_i32_e32 v41, 31, v40
	v_lshlrev_b64 v[40:41], 11, v[40:41]
	v_lshl_add_u64 v[40:41], v[4:5], 0, v[40:41]
	global_load_dwordx2 v[50:51], v[40:41], off offset:1024
	s_waitcnt vmcnt(0)
	v_cndmask_b32_e64 v78, 0, v51, s[14:15]
	v_cndmask_b32_e64 v79, 0, v50, s[14:15]
	v_add_f32_e32 v50, 0, v80
	v_add_f32_e32 v51, 0, v81
	v_add_f32_e32 v50, v50, v90
	v_add_f32_e32 v51, v51, v55
	v_add_f32_e32 v97, v50, v95
	v_add_f32_e32 v98, v51, v57
	v_max_i32_e32 v50, 4, v46
	v_min_i32_e32 v51, 0x3ffc, v46
	v_sub_u32_e32 v50, v51, v50
	v_add_u32_e32 v50, 8, v50
	v_cvt_f32_i32_e32 v50, v50
	v_sub_f32_e32 v81, v67, v81
	v_sub_f32_e32 v55, v69, v55
	v_sub_f32_e32 v57, v71, v57
	v_div_scale_f32 v51, s[2:3], v50, v50, 1.0
	v_rcp_f32_e32 v52, v51
	s_nop 0
	v_fma_f32 v102, -v51, v52, 1.0
	v_fmac_f32_e32 v52, v102, v52
	v_div_scale_f32 v102, vcc, 1.0, v50, 1.0
	v_mul_f32_e32 v103, v102, v52
	v_fma_f32 v104, -v51, v103, v102
	v_fmac_f32_e32 v103, v104, v52
	v_fma_f32 v51, -v51, v103, v102
	v_div_fmas_f32 v51, v51, v52, v103
	v_lshlrev_b32_e32 v103, 16, v59
	v_and_b32_e32 v59, 0xffff0000, v59
	v_div_fixup_f32 v102, v51, v50, 1.0
	v_lshlrev_b32_e32 v50, 16, v73
	v_and_b32_e32 v51, 0xffff0000, v73
	v_add_f32_e32 v73, v98, v59
	v_lshlrev_b32_e32 v98, 16, v58
	v_and_b32_e32 v58, 0xffff0000, v58
	v_lshlrev_b32_e32 v52, 16, v72
	v_add_f32_e32 v104, v53, v98
	v_and_b32_e32 v53, 0xffff0000, v72
	v_add_f32_e32 v72, v101, v58
	v_max_i32_e32 v101, 4, v47
	v_sub_u32_e32 v101, v105, v101
	v_add_u32_e32 v101, 8, v101
	v_cvt_f32_i32_e32 v101, v101
	v_sub_f32_e32 v58, v53, v58
	v_add_f32_e32 v97, v97, v103
	v_sub_f32_e32 v59, v51, v59
	v_div_scale_f32 v105, s[2:3], v101, v101, 1.0
	v_rcp_f32_e32 v106, v105
	s_nop 0
	v_fma_f32 v107, -v105, v106, 1.0
	v_fmac_f32_e32 v106, v107, v106
	v_div_scale_f32 v107, vcc, 1.0, v101, 1.0
	v_mul_f32_e32 v108, v107, v106
	v_fma_f32 v109, -v105, v108, v107
	v_fmac_f32_e32 v108, v109, v106
	v_max_i32_e32 v109, 4, v48
	v_sub_u32_e32 v109, v110, v109
	v_add_u32_e32 v109, 8, v109
	v_cvt_f32_i32_e32 v109, v109
	v_fma_f32 v105, -v105, v108, v107
	v_div_fmas_f32 v105, v105, v106, v108
	v_lshlrev_b32_e32 v108, 16, v60
	v_div_scale_f32 v110, s[2:3], v109, v109, 1.0
	v_rcp_f32_e32 v111, v110
	v_and_b32_e32 v60, 0xffff0000, v60
	v_add_f32_e32 v72, v72, v60
	v_lshlrev_b32_e32 v107, 16, v74
	v_fma_f32 v112, -v110, v111, 1.0
	v_fmac_f32_e32 v111, v112, v111
	v_div_scale_f32 v112, vcc, 1.0, v109, 1.0
	v_mul_f32_e32 v113, v112, v111
	v_fma_f32 v114, -v110, v113, v112
	v_fmac_f32_e32 v113, v114, v111
	v_max_i32_e32 v114, 4, v49
	v_sub_u32_e32 v114, v115, v114
	v_add_u32_e32 v114, 8, v114
	v_cvt_f32_i32_e32 v114, v114
	v_fma_f32 v110, -v110, v113, v112
; __device__ __forceinline__ unsigned pk2(float lo, float hi) { unsigned r; asm("v_cvt_pk_bf16_f32 %0, %1, %2" : "=v"(r) : "v"(lo), "v"(hi)); return r; }
; __device__ __forceinline__ float bflo(unsigned u) { return __uint_as_float(u << 16); }
; __device__ __forceinline__ float bfhi(unsigned u) { return __uint_as_float(u & 0xFFFF0000u); }
; template <int J> __device__ __forceinline__ void pool_group(const bf16_t* hbuf, bf16_t* pl, int c0, int lane) {
;     ...
;     float s0 = 0.f, s1 = 0.f, s2 = 0.f, s3 = 0.f;
; #pragma unroll
;     for (int k = 0; k < W; ++k) { s0 += bflo(raw[k].x); s1 += bfhi(raw[k].x); s2 += bflo(raw[k].y); s3 += bfhi(raw[k].y); }
; #pragma unroll
;     for (int i = 0; i < 8; ++i) {
;         const int t = c0 + i; int lo = t - H, hi = t + H - 1; lo = lo < 0 ? 0 : lo; hi = hi > SEQ - 1 ? SEQ - 1 : hi;
;         const float ic = 1.f / (float)(hi - lo + 1);
;         const u32x2 self = raw[i + H];
;         u32x2 o; o.x = pk2(s0 * ic - bflo(self.x), s1 * ic - bfhi(self.x)); o.y = pk2(s2 * ic - bflo(self.y), s3 * ic - bfhi(self.y));
;         *((u32x2*)(pl + ((size_t)J * SEQ + t) * 256) + lane) = o;
;         if (i < 7) { s0 += bflo(raw[i + W].x) - bflo(raw[i].x); s1 += bfhi(raw[i + W].x) - bfhi(raw[i].x); s2 += bflo(raw[i + W].y) - bflo(raw[i].y); s3 += bfhi(raw[i + W].y) - bfhi(raw[i].y); }
	v_div_fmas_f32 v110, v110, v111, v113
	v_lshlrev_b32_e32 v113, 16, v62
	v_div_scale_f32 v115, s[2:3], v114, v114, 1.0
	v_rcp_f32_e32 v116, v115
	v_and_b32_e32 v62, 0xffff0000, v62
	v_add_f32_e32 v72, v72, v62
	v_and_b32_e32 v74, 0xffff0000, v74
	v_fma_f32 v117, -v115, v116, 1.0
	v_fmac_f32_e32 v116, v117, v116
	v_div_scale_f32 v117, vcc, 1.0, v114, 1.0
	v_mul_f32_e32 v118, v117, v116
	v_fma_f32 v119, -v115, v118, v117
	v_fmac_f32_e32 v118, v119, v116
	v_fma_f32 v115, -v115, v118, v117
	v_div_fmas_f32 v115, v115, v116, v118
	v_div_fixup_f32 v114, v115, v114, 1.0
	v_and_b32_e32 v115, 0xffff0000, v43
	v_add_f32_e32 v72, v72, v115
	v_add_f32_e32 v72, v72, v64
	v_fma_f32 v117, v84, v72, -v60
	v_add_f32_e32 v72, v72, v83
	v_add_f32_e32 v54, v72, v54
	v_fma_f32 v83, v89, v72, -v62
	v_fma_f32 v72, v94, v54, -v115
	v_add_f32_e32 v54, v54, v56
	v_div_fixup_f32 v101, v105, v101, 1.0
	v_add_f32_e32 v104, v104, v108
	v_lshlrev_b32_e32 v112, 16, v76
	v_and_b32_e32 v76, 0xffff0000, v76
	v_fma_f32 v56, v102, v54, -v64
	v_add_f32_e32 v54, v54, v58
	v_sub_f32_e32 v60, v74, v60
	v_div_fixup_f32 v109, v110, v109, 1.0
	v_add_f32_e32 v104, v104, v113
	v_fma_f32 v58, v101, v54, -v66
	v_add_f32_e32 v54, v54, v60
	v_sub_f32_e32 v62, v76, v62
	v_lshlrev_b32_e32 v43, 16, v43
	v_fma_f32 v60, v109, v54, -v68
	v_add_f32_e32 v54, v54, v62
	v_add_f32_e32 v66, v104, v43
	v_fma_f32 v62, v114, v54, -v70
	v_add_f32_e32 v66, v66, v87
	v_sub_f32_e32 v70, v88, v82
	v_and_b32_e32 v116, 0xffff0000, v78
	v_fma_f32 v68, v84, v66, -v108
	v_add_f32_e32 v66, v66, v70
	v_sub_f32_e32 v74, v92, v93
	v_sub_f32_e32 v64, v116, v115
	v_fma_f32 v70, v89, v66, -v113
	v_add_f32_e32 v66, v66, v74
	v_sub_f32_e32 v76, v99, v100
	v_add_f32_e32 v64, v54, v64
	v_lshlrev_b32_e32 v54, 16, v78
	v_fma_f32 v74, v94, v66, -v43
	v_add_f32_e32 v66, v66, v76
	v_sub_f32_e32 v78, v52, v98
	v_fma_f32 v76, v102, v66, -v87
	v_add_f32_e32 v66, v66, v78
	v_sub_f32_e32 v82, v107, v108
	v_lshlrev_b32_e32 v105, 16, v61
	v_and_b32_e32 v61, 0xffff0000, v61
	v_fma_f32 v78, v101, v66, -v88
	v_add_f32_e32 v66, v66, v82
	v_sub_f32_e32 v87, v112, v113
	v_add_f32_e32 v73, v73, v61
	v_lshlrev_b32_e32 v110, 16, v63
	v_and_b32_e32 v63, 0xffff0000, v63
	v_fma_f32 v82, v109, v66, -v92
	v_add_f32_e32 v66, v66, v87
	v_sub_f32_e32 v43, v54, v43
	v_add_f32_e32 v73, v73, v63
	v_fma_f32 v87, v114, v66, -v99
	v_add_f32_e32 v66, v66, v43
	v_and_b32_e32 v43, 0xffff0000, v42
	v_add_f32_e32 v73, v73, v43
	v_add_f32_e32 v73, v73, v65
	v_fma_f32 v88, v84, v73, -v61
	v_add_f32_e32 v73, v73, v81
	v_add_f32_e32 v55, v73, v55
	v_fma_f32 v81, v89, v73, -v63
	v_fma_f32 v73, v94, v55, -v43
	v_add_f32_e32 v55, v55, v57
	v_lshlrev_b32_e32 v106, 16, v75
	v_add_f32_e32 v97, v97, v105
	v_and_b32_e32 v75, 0xffff0000, v75
	v_fma_f32 v57, v102, v55, -v65
	v_add_f32_e32 v55, v55, v59
	v_lshlrev_b32_e32 v111, 16, v77
	v_add_f32_e32 v97, v97, v110
	v_and_b32_e32 v77, 0xffff0000, v77
	v_fma_f32 v59, v101, v55, -v67
	v_sub_f32_e32 v61, v75, v61
	v_lshlrev_b32_e32 v67, 16, v42
	v_and_b32_e32 v54, 0xffff0000, v79
	v_add_f32_e32 v55, v55, v61
	v_sub_f32_e32 v63, v77, v63
	v_add_f32_e32 v42, v97, v67
	v_fma_f32 v61, v109, v55, -v69
	v_add_f32_e32 v55, v55, v63
	v_sub_f32_e32 v43, v54, v43
	v_add_f32_e32 v42, v42, v86
	v_sub_f32_e32 v54, v85, v80
	v_add_f32_e32 v65, v55, v43
	v_fma_f32 v43, v84, v42, -v105
	v_add_f32_e32 v42, v42, v54
	v_sub_f32_e32 v54, v91, v90
	v_fma_f32 v63, v114, v55, -v71
	v_fma_f32 v71, v89, v42, -v110
	v_add_f32_e32 v42, v42, v54
	v_sub_f32_e32 v54, v96, v95
	v_fma_f32 v75, v94, v42, -v67
	v_add_f32_e32 v42, v42, v54
	v_sub_f32_e32 v54, v50, v103
	v_fma_f32 v77, v102, v42, -v86
	v_add_f32_e32 v42, v42, v54
	v_sub_f32_e32 v54, v106, v105
	v_lshlrev_b32_e32 v69, 16, v79
	v_fma_f32 v79, v101, v42, -v85
	v_add_f32_e32 v42, v42, v54
	v_sub_f32_e32 v54, v111, v110
	s_mov_b32 s2, 0x4f7b9000
	v_add_f32_e32 v84, v42, v54
	v_add_co_u32_e32 v54, vcc, s2, v10
	v_fma_f32 v80, v109, v42, -v91
	v_cvt_pk_bf16_f32 v42, v43, v88
	v_cvt_pk_bf16_f32 v43, v68, v117
	s_nop 0
	v_addc_co_u32_e32 v55, vcc, 0, v11, vcc
	global_store_dwordx2 v[54:55], v[42:43], off
	v_cvt_pk_bf16_f32 v43, v70, v83
	v_cvt_pk_bf16_f32 v42, v71, v81
	global_store_dwordx2 v[54:55], v[42:43], off offset:512
	v_cvt_pk_bf16_f32 v43, v74, v72
	v_cvt_pk_bf16_f32 v42, v75, v73
	global_store_dwordx2 v[54:55], v[42:43], off offset:1024
	v_cvt_pk_bf16_f32 v43, v76, v56
	v_cvt_pk_bf16_f32 v42, v77, v57
	global_store_dwordx2 v[54:55], v[42:43], off offset:1536
	v_cvt_pk_bf16_f32 v43, v78, v58
	v_cvt_pk_bf16_f32 v42, v79, v59
	global_store_dwordx2 v[54:55], v[42:43], off offset:2048
	v_cvt_pk_bf16_f32 v43, v82, v60
	v_cvt_pk_bf16_f32 v42, v80, v61
	global_store_dwordx2 v[54:55], v[42:43], off offset:2560
	v_cvt_pk_bf16_f32 v43, v87, v62
	v_fma_f32 v85, v114, v84, -v96
	v_cvt_pk_bf16_f32 v42, v85, v63
	global_store_dwordx2 v[54:55], v[42:43], off offset:3072
	v_max_i32_e32 v43, 4, v3
	v_min_i32_e32 v56, 0x3ffc, v3
	v_sub_u32_e32 v43, v56, v43
	v_add_u32_e32 v43, 8, v43
	v_cvt_f32_i32_e32 v43, v43
	v_sub_f32_e32 v42, v69, v67
	v_add_f32_e32 v42, v84, v42
	v_div_scale_f32 v56, s[2:3], v43, v43, 1.0
	v_rcp_f32_e32 v57, v56
	s_nop 0
	v_fma_f32 v58, -v56, v57, 1.0
	v_fmac_f32_e32 v57, v58, v57
	v_div_scale_f32 v58, vcc, 1.0, v43, 1.0
	v_mul_f32_e32 v59, v58, v57
	v_fma_f32 v60, -v56, v59, v58
	v_fmac_f32_e32 v59, v60, v57
	v_fma_f32 v56, -v56, v59, v58
	v_div_fmas_f32 v56, v56, v57, v59
	v_div_fixup_f32 v43, v56, v43, 1.0
	v_fma_f32 v42, v43, v42, -v50
	v_fma_f32 v50, v43, v65, -v51
	v_cvt_pk_bf16_f32 v42, v42, v50
	v_fma_f32 v50, v43, v66, -v52
	v_fma_f32 v43, v43, v64, -v53
	v_cvt_pk_bf16_f32 v43, v50, v43
	global_store_dwordx2 v[54:55], v[42:43], off offset:3584
	global_load_dwordx2 v[120:121], v[34:35], off offset:1536
	global_load_dwordx2 v[122:123], v[36:37], off offset:1536
	global_load_dwordx2 v[124:125], v[30:31], off offset:1536
	global_load_dwordx2 v[126:127], v[12:13], off offset:1536
	global_load_dwordx2 v[128:129], v[14:15], off offset:1536
	global_load_dwordx2 v[130:131], v[16:17], off offset:1536
	global_load_dwordx2 v[132:133], v[18:19], off offset:1536
	global_load_dwordx2 v[134:135], v[20:21], off offset:1536
	global_load_dwordx2 v[136:137], v[22:23], off offset:1536
	global_load_dwordx2 v[138:139], v[24:25], off offset:1536
	global_load_dwordx2 v[140:141], v[26:27], off offset:1536
	global_load_dwordx2 v[142:143], v[28:29], off offset:1536
	global_load_dwordx2 v[144:145], v[32:33], off offset:1536
	global_load_dwordx2 v[146:147], v[38:39], off offset:1536
	global_load_dwordx2 v[148:149], v[40:41], off offset:1536
	v_add_u32_e32 v42, -8, v2
	v_cmp_gt_u32_e32 vcc, s33, v42
	s_waitcnt vmcnt(0)
; template <int J> __device__ __forceinline__ void pool_group(const bf16_t* hbuf, bf16_t* pl, int c0, int lane) {
;     ...
;     for (int k = 0; k < NR; ++k) { const int tt = c0 - H + k; const bool ok = tt >= 0 && tt < SEQ; const int tc = ok ? tt : c0;
;         raw[k] = *((const u32x2*)(hbuf + (size_t)tc * D + 256 * J) + lane); if (!ok) raw[k] = (u32x2){0u, 0u}; }
	v_mov_b64_e32 v[34:35], v[120:121]
	s_nop 0
	s_waitcnt vmcnt(0)
	v_mov_b64_e32 v[36:37], v[122:123]
	v_cndmask_b32_e32 v42, v2, v42, vcc
	v_ashrrev_i32_e32 v43, 31, v42
	v_lshlrev_b64 v[42:43], 11, v[42:43]
	v_lshl_add_u64 v[42:43], v[4:5], 0, v[42:43]
	global_load_dwordx2 v[42:43], v[42:43], off offset:1536
	s_waitcnt vmcnt(0)
	v_cndmask_b32_e32 v57, 0, v42, vcc
	v_add_u32_e32 v42, -7, v2
	v_cndmask_b32_e32 v56, 0, v43, vcc
	v_cmp_gt_u32_e32 vcc, s33, v42
	s_waitcnt vmcnt(0)
	v_mov_b64_e32 v[30:31], v[124:125]
	v_lshlrev_b32_e32 v76, 16, v56
	v_cndmask_b32_e32 v42, v2, v42, vcc
	v_ashrrev_i32_e32 v43, 31, v42
	v_lshlrev_b64 v[42:43], 11, v[42:43]
	v_lshl_add_u64 v[42:43], v[4:5], 0, v[42:43]
	global_load_dwordx2 v[50:51], v[42:43], off offset:1536
	v_add_u32_e32 v43, -6, v2
	s_waitcnt vmcnt(0)
	v_mov_b64_e32 v[12:13], v[126:127]
	v_and_b32_e32 v56, 0xffff0000, v56
	v_add_f32_e32 v78, 0, v56
	v_add_f32_e32 v77, 0, v76
	s_waitcnt vmcnt(2)
	v_cndmask_b32_e64 v31, 0, v31, s[6:7]
	v_cndmask_b32_e64 v30, 0, v30, s[6:7]
	s_waitcnt vmcnt(1)
	v_cndmask_b32_e32 v42, 0, v51, vcc
	v_cndmask_b32_e32 v50, 0, v50, vcc
	v_cmp_gt_u32_e32 vcc, s33, v43
	v_cndmask_b32_e64 v51, 0, v34, s[8:9]
	v_cndmask_b32_e64 v34, 0, v37, s[10:11]
	v_cndmask_b32_e32 v52, v2, v43, vcc
	v_ashrrev_i32_e32 v53, 31, v52
	v_lshlrev_b64 v[52:53], 11, v[52:53]
	v_lshl_add_u64 v[52:53], v[4:5], 0, v[52:53]
	global_load_dwordx2 v[54:55], v[52:53], off offset:1536
	v_add_u32_e32 v43, -5, v2
	s_waitcnt vmcnt(1)
	v_cndmask_b32_e64 v37, 0, v12, s[16:17]
	s_waitcnt vmcnt(0)
	v_cndmask_b32_e32 v52, 0, v55, vcc
	v_cndmask_b32_e32 v53, 0, v54, vcc
	v_cmp_gt_u32_e32 vcc, s33, v43
	s_nop 1
	v_cndmask_b32_e32 v54, v2, v43, vcc
	v_ashrrev_i32_e32 v55, 31, v54
	v_lshlrev_b64 v[54:55], 11, v[54:55]
	v_lshl_add_u64 v[54:55], v[4:5], 0, v[54:55]
	global_load_dwordx2 v[58:59], v[54:55], off offset:1536
	v_cndmask_b32_e64 v43, 0, v35, s[8:9]
	v_cndmask_b32_e64 v35, 0, v36, s[10:11]
	v_cndmask_b32_e64 v36, 0, v13, s[16:17]
	s_waitcnt vmcnt(0)
	v_mov_b64_e32 v[12:13], v[128:129]
	v_lshlrev_b32_e32 v79, 16, v36
	v_and_b32_e32 v36, 0xffff0000, v36
	s_waitcnt vmcnt(1)
	v_cndmask_b32_e32 v54, 0, v59, vcc
	v_cndmask_b32_e32 v55, 0, v58, vcc
	s_waitcnt vmcnt(0)
	v_cndmask_b32_e64 v58, 0, v13, s[0:1]
	v_cndmask_b32_e64 v59, 0, v12, s[0:1]
	s_waitcnt vmcnt(0)
	v_mov_b64_e32 v[12:13], v[130:131]
	v_lshlrev_b32_e32 v80, 16, v58
	v_and_b32_e32 v58, 0xffff0000, v58
	s_waitcnt vmcnt(0)
	v_cndmask_b32_e64 v17, 0, v13, s[0:1]
	v_cndmask_b32_e64 v60, 0, v12, s[0:1]
	s_waitcnt vmcnt(0)
	v_mov_b64_e32 v[12:13], v[132:133]
	v_lshlrev_b32_e32 v81, 16, v17
	v_and_b32_e32 v82, 0xffff0000, v17
	v_min_i32_e32 v17, 0x3ff8, v2
	s_waitcnt vmcnt(0)
	v_cndmask_b32_e64 v61, 0, v13, s[0:1]
	v_cndmask_b32_e64 v62, 0, v12, s[0:1]
	s_waitcnt vmcnt(0)
	v_mov_b64_e32 v[12:13], v[134:135]
	v_lshlrev_b32_e32 v83, 16, v61
	v_and_b32_e32 v61, 0xffff0000, v61
	s_waitcnt vmcnt(0)
	v_cndmask_b32_e64 v63, 0, v13, s[0:1]
	v_cndmask_b32_e64 v64, 0, v12, s[0:1]
	s_waitcnt vmcnt(0)
	v_mov_b64_e32 v[12:13], v[136:137]
	v_lshlrev_b32_e32 v84, 16, v63
	v_and_b32_e32 v63, 0xffff0000, v63
	s_waitcnt vmcnt(0)
	v_cndmask_b32_e64 v65, 0, v13, s[0:1]
	v_cndmask_b32_e64 v66, 0, v12, s[0:1]
	s_waitcnt vmcnt(0)
	v_mov_b64_e32 v[12:13], v[138:139]
	v_lshlrev_b32_e32 v85, 16, v65
	v_and_b32_e32 v65, 0xffff0000, v65
	v_lshlrev_b32_e32 v24, 16, v59
	v_and_b32_e32 v59, 0xffff0000, v59
	v_lshlrev_b32_e32 v25, 16, v60
	v_and_b32_e32 v60, 0xffff0000, v60
	s_waitcnt vmcnt(0)
	v_cndmask_b32_e64 v67, 0, v13, s[0:1]
	v_cndmask_b32_e64 v68, 0, v12, s[0:1]
	s_waitcnt vmcnt(0)
	v_mov_b64_e32 v[12:13], v[140:141]
	v_lshlrev_b32_e32 v86, 16, v67
	v_and_b32_e32 v67, 0xffff0000, v67
	v_lshlrev_b32_e32 v26, 16, v62
	v_and_b32_e32 v62, 0xffff0000, v62
	v_lshlrev_b32_e32 v27, 16, v64
	v_and_b32_e32 v64, 0xffff0000, v64
	s_waitcnt vmcnt(0)
	v_cndmask_b32_e64 v69, 0, v13, s[0:1]
	v_cndmask_b32_e64 v70, 0, v12, s[0:1]
	s_waitcnt vmcnt(0)
	v_mov_b64_e32 v[12:13], v[142:143]
	v_lshlrev_b32_e32 v87, 16, v69
	v_and_b32_e32 v69, 0xffff0000, v69
	v_lshlrev_b32_e32 v29, 16, v37
	v_and_b32_e32 v37, 0xffff0000, v37
	v_lshlrev_b32_e32 v28, 16, v66
	v_and_b32_e32 v66, 0xffff0000, v66
	s_waitcnt vmcnt(0)
	v_cndmask_b32_e64 v18, 0, v13, s[0:1]
	v_cndmask_b32_e64 v16, 0, v12, s[0:1]
	s_waitcnt vmcnt(0)
	v_mov_b64_e32 v[12:13], v[144:145]
	s_waitcnt vmcnt(0)
	v_mov_b64_e32 v[14:15], v[146:147]
	s_waitcnt vmcnt(0)
	v_mov_b64_e32 v[22:23], v[148:149]
	v_lshlrev_b32_e32 v32, 16, v68
	v_and_b32_e32 v68, 0xffff0000, v68
	v_lshlrev_b32_e32 v33, 16, v70
	v_and_b32_e32 v70, 0xffff0000, v70
	s_waitcnt vmcnt(2)
	v_cndmask_b32_e64 v13, 0, v13, s[4:5]
	s_waitcnt vmcnt(1)
	v_cndmask_b32_e64 v20, 0, v15, s[12:13]
	v_add_u32_e32 v15, 11, v2
	v_cmp_gt_u32_e32 vcc, s33, v15
	s_waitcnt vmcnt(0)
	v_cndmask_b32_e64 v19, 0, v22, s[14:15]
	v_cndmask_b32_e64 v21, 0, v14, s[12:13]
	v_cndmask_b32_e32 v22, v2, v15, vcc
	v_cndmask_b32_e64 v14, 0, v23, s[14:15]
	v_ashrrev_i32_e32 v23, 31, v22
	v_lshlrev_b64 v[22:23], 11, v[22:23]
	v_lshl_add_u64 v[22:23], v[4:5], 0, v[22:23]
	global_load_dwordx2 v[22:23], v[22:23], off offset:1536
	v_add_u32_e32 v15, 12, v2
	v_cndmask_b32_e64 v12, 0, v12, s[4:5]
	s_waitcnt vmcnt(0)
	v_cndmask_b32_e32 v38, 0, v23, vcc
	v_cndmask_b32_e32 v39, 0, v22, vcc
	v_cmp_gt_u32_e32 vcc, s33, v15
	s_nop 1
	v_cndmask_b32_e32 v22, v2, v15, vcc
	v_ashrrev_i32_e32 v23, 31, v22
	v_lshlrev_b64 v[22:23], 11, v[22:23]
	v_lshl_add_u64 v[22:23], v[4:5], 0, v[22:23]
	global_load_dwordx2 v[22:23], v[22:23], off offset:1536
	v_add_u32_e32 v15, 13, v2
	s_waitcnt vmcnt(0)
; __device__ __forceinline__ float bflo(unsigned u) { return __uint_as_float(u << 16); }
; __device__ __forceinline__ float bfhi(unsigned u) { return __uint_as_float(u & 0xFFFF0000u); }
; template <int J> __device__ __forceinline__ void pool_group(const bf16_t* hbuf, bf16_t* pl, int c0, int lane) {
;     ...
;     for (int k = 0; k < NR; ++k) { const int tt = c0 - H + k; const bool ok = tt >= 0 && tt < SEQ; const int tc = ok ? tt : c0;
;         raw[k] = *((const u32x2*)(hbuf + (size_t)tc * D + 256 * J) + lane); if (!ok) raw[k] = (u32x2){0u, 0u}; }
;     float s0 = 0.f, s1 = 0.f, s2 = 0.f, s3 = 0.f;
; #pragma unroll
;     for (int k = 0; k < W; ++k) { s0 += bflo(raw[k].x); s1 += bfhi(raw[k].x); s2 += bflo(raw[k].y); s3 += bfhi(raw[k].y); }
; #pragma unroll
;     for (int i = 0; i < 8; ++i) {
;         const int t = c0 + i; int lo = t - H, hi = t + H - 1; lo = lo < 0 ? 0 : lo; hi = hi > SEQ - 1 ? SEQ - 1 : hi;
;         const float ic = 1.f / (float)(hi - lo + 1);
	v_cndmask_b32_e32 v40, 0, v23, vcc
	v_cndmask_b32_e32 v41, 0, v22, vcc
	v_cmp_gt_u32_e32 vcc, s33, v15
	s_nop 1
	v_cndmask_b32_e32 v22, v2, v15, vcc
	v_ashrrev_i32_e32 v23, 31, v22
	v_lshlrev_b64 v[22:23], 11, v[22:23]
	v_lshl_add_u64 v[22:23], v[4:5], 0, v[22:23]
	global_load_dwordx2 v[22:23], v[22:23], off offset:1536
	v_add_u32_e32 v15, 14, v2
	s_waitcnt vmcnt(0)
	v_cndmask_b32_e32 v71, 0, v23, vcc
	v_cndmask_b32_e32 v72, 0, v22, vcc
	v_cmp_gt_u32_e32 vcc, s33, v15
	s_nop 1
	v_cndmask_b32_e32 v22, v2, v15, vcc
	v_ashrrev_i32_e32 v23, 31, v22
	v_lshlrev_b64 v[22:23], 11, v[22:23]
	v_lshl_add_u64 v[22:23], v[4:5], 0, v[22:23]
	global_load_dwordx2 v[22:23], v[22:23], off offset:1536
	v_max_i32_e32 v15, 8, v2
	v_sub_u32_e32 v15, v17, v15
	v_add_u32_e32 v15, 16, v15
	v_cvt_f32_i32_e32 v15, v15
	v_add_u32_e32 v2, s40, v2
	v_div_scale_f32 v17, s[0:1], v15, v15, 1.0
	v_rcp_f32_e32 v88, v17
	s_waitcnt vmcnt(0)
	v_cndmask_b32_e32 v73, 0, v23, vcc
	v_fma_f32 v89, -v17, v88, 1.0
	v_cndmask_b32_e32 v23, 0, v22, vcc
	v_fmac_f32_e32 v88, v89, v88
	v_div_scale_f32 v89, vcc, 1.0, v15, 1.0
	v_mul_f32_e32 v90, v89, v88
	v_fma_f32 v91, -v17, v90, v89
	v_fmac_f32_e32 v90, v91, v88
	v_max_i32_e32 v91, 8, v45
	v_min_i32_e32 v45, 0x3ff8, v45
	v_sub_u32_e32 v45, v45, v91
	v_add_u32_e32 v45, 16, v45
	v_cvt_f32_i32_e32 v45, v45
	v_fma_f32 v17, -v17, v90, v89
	v_div_fmas_f32 v17, v17, v88, v90
	v_div_fixup_f32 v88, v17, v15, 1.0
	v_div_scale_f32 v91, s[0:1], v45, v45, 1.0
	v_rcp_f32_e32 v92, v91
	v_lshlrev_b32_e32 v15, 16, v16
	v_and_b32_e32 v17, 0xffff0000, v16
	v_lshlrev_b32_e32 v16, 16, v18
	v_fma_f32 v93, -v91, v92, 1.0
	v_fmac_f32_e32 v92, v93, v92
	v_div_scale_f32 v93, vcc, 1.0, v45, 1.0
	v_mul_f32_e32 v94, v93, v92
	v_fma_f32 v95, -v91, v94, v93
	v_fmac_f32_e32 v94, v95, v92
	v_max_i32_e32 v95, 8, v44
	v_min_i32_e32 v44, 0x3ff8, v44
	v_sub_u32_e32 v44, v44, v95
	v_add_u32_e32 v44, 16, v44
	v_cvt_f32_i32_e32 v44, v44
	v_fma_f32 v91, -v91, v94, v93
	v_div_fmas_f32 v91, v91, v92, v94
	v_lshlrev_b32_e32 v94, 16, v42
	v_div_scale_f32 v95, s[0:1], v44, v44, 1.0
	v_rcp_f32_e32 v96, v95
	v_and_b32_e32 v42, 0xffff0000, v42
	v_add_f32_e32 v78, v78, v42
	v_add_f32_e32 v77, v77, v94
	v_fma_f32 v97, -v95, v96, 1.0
	v_fmac_f32_e32 v96, v97, v96
	v_div_scale_f32 v97, vcc, 1.0, v44, 1.0
	v_mul_f32_e32 v98, v97, v96
	v_fma_f32 v99, -v95, v98, v97
	v_fmac_f32_e32 v98, v99, v96
	v_max_i32_e32 v99, 8, v46
	v_min_i32_e32 v46, 0x3ff8, v46
	v_sub_u32_e32 v46, v46, v99
	v_add_u32_e32 v46, 16, v46
	v_cvt_f32_i32_e32 v46, v46
	v_fma_f32 v95, -v95, v98, v97
	v_div_fmas_f32 v95, v95, v96, v98
	v_lshlrev_b32_e32 v98, 16, v52
	v_div_scale_f32 v99, s[0:1], v46, v46, 1.0
	v_rcp_f32_e32 v100, v99
	v_and_b32_e32 v52, 0xffff0000, v52
	v_add_f32_e32 v78, v78, v52
	v_add_f32_e32 v77, v77, v98
	v_fma_f32 v101, -v99, v100, 1.0
	v_fmac_f32_e32 v100, v101, v100
	v_div_scale_f32 v101, vcc, 1.0, v46, 1.0
	v_mul_f32_e32 v102, v101, v100
	v_fma_f32 v103, -v99, v102, v101
	v_fmac_f32_e32 v102, v103, v100
	v_max_i32_e32 v103, 8, v47
	v_min_i32_e32 v47, 0x3ff8, v47
	v_sub_u32_e32 v47, v47, v103
	v_add_u32_e32 v47, 16, v47
	v_cvt_f32_i32_e32 v47, v47
	v_fma_f32 v99, -v99, v102, v101
	v_div_fmas_f32 v99, v99, v100, v102
	v_lshlrev_b32_e32 v102, 16, v54
	v_div_scale_f32 v103, s[0:1], v47, v47, 1.0
	v_rcp_f32_e32 v104, v103
	v_and_b32_e32 v54, 0xffff0000, v54
	v_add_f32_e32 v78, v78, v54
	v_add_f32_e32 v77, v77, v102
	v_fma_f32 v105, -v103, v104, 1.0
	v_fmac_f32_e32 v104, v105, v104
	v_div_scale_f32 v105, vcc, 1.0, v47, 1.0
	v_mul_f32_e32 v106, v105, v104
	v_fma_f32 v107, -v103, v106, v105
	v_fmac_f32_e32 v106, v107, v104
	v_max_i32_e32 v107, 8, v48
	v_min_i32_e32 v48, 0x3ff8, v48
	v_sub_u32_e32 v48, v48, v107
	v_add_u32_e32 v48, 16, v48
	v_cvt_f32_i32_e32 v48, v48
	v_fma_f32 v103, -v103, v106, v105
	v_div_fmas_f32 v103, v103, v104, v106
	v_lshlrev_b32_e32 v106, 16, v43
	v_div_scale_f32 v107, s[0:1], v48, v48, 1.0
	v_rcp_f32_e32 v108, v107
	v_and_b32_e32 v43, 0xffff0000, v43
	v_add_f32_e32 v78, v78, v43
	v_add_f32_e32 v77, v77, v106
	v_fma_f32 v109, -v107, v108, 1.0
	v_fmac_f32_e32 v108, v109, v108
	v_div_scale_f32 v109, vcc, 1.0, v48, 1.0
	v_mul_f32_e32 v110, v109, v108
	v_fma_f32 v111, -v107, v110, v109
	v_fmac_f32_e32 v110, v111, v108
	v_max_i32_e32 v111, 8, v49
	v_min_i32_e32 v49, 0x3ff8, v49
	v_sub_u32_e32 v49, v49, v111
	v_add_u32_e32 v49, 16, v49
	v_cvt_f32_i32_e32 v49, v49
	v_fma_f32 v107, -v107, v110, v109
	v_div_fmas_f32 v107, v107, v108, v110
	v_lshlrev_b32_e32 v110, 16, v34
	v_div_scale_f32 v111, s[0:1], v49, v49, 1.0
	v_rcp_f32_e32 v112, v111
	v_and_b32_e32 v34, 0xffff0000, v34
	v_add_f32_e32 v78, v78, v34
	v_lshlrev_b32_e32 v105, 16, v40
	v_fma_f32 v113, -v111, v112, 1.0
	v_fmac_f32_e32 v112, v113, v112
	v_div_scale_f32 v113, vcc, 1.0, v49, 1.0
	v_mul_f32_e32 v114, v113, v112
	v_fma_f32 v115, -v111, v114, v113
	v_fmac_f32_e32 v114, v115, v112
	v_fma_f32 v111, -v111, v114, v113
	v_div_fmas_f32 v111, v111, v112, v114
	v_div_fixup_f32 v49, v111, v49, 1.0
	v_and_b32_e32 v111, 0xffff0000, v31
	v_add_f32_e32 v78, v78, v111
	v_and_b32_e32 v40, 0xffff0000, v40
	v_add_f32_e32 v77, v77, v110
	v_add_f32_e32 v36, v78, v36
	v_lshlrev_b32_e32 v31, 16, v31
	v_add_f32_e32 v36, v36, v58
	v_sub_f32_e32 v40, v40, v43
	v_add_f32_e32 v43, v77, v31
	v_add_f32_e32 v36, v36, v82
	v_add_f32_e32 v43, v43, v79
	v_add_f32_e32 v36, v36, v61
	v_add_f32_e32 v43, v43, v80
	v_add_f32_e32 v36, v36, v63
	v_add_f32_e32 v43, v43, v81
	v_add_f32_e32 v36, v36, v65
	v_add_f32_e32 v43, v43, v83
	v_add_f32_e32 v36, v36, v67
	v_add_f32_e32 v43, v43, v84
	v_lshlrev_b32_e32 v90, 16, v13
	v_and_b32_e32 v13, 0xffff0000, v13
; __device__ __forceinline__ unsigned pk2(float lo, float hi) { unsigned r; asm("v_cvt_pk_bf16_f32 %0, %1, %2" : "=v"(r) : "v"(lo), "v"(hi)); return r; }
; __device__ __forceinline__ int get_tid() { int t = threadIdx.x; asm volatile("" : "+v"(t)); return t; }
; __device__ __forceinline__ int get_bid() { int b = blockIdx.x; asm volatile("" : "+s"(b)); return b; }
; __device__ __forceinline__ float bflo(unsigned u) { return __uint_as_float(u << 16); }
; __device__ __forceinline__ float bfhi(unsigned u) { return __uint_as_float(u & 0xFFFF0000u); }
; template <int J> __device__ __forceinline__ void pool_group(const bf16_t* hbuf, bf16_t* pl, int c0, int lane) {
;     ...
;     for (int i = 0; i < 8; ++i) {
;         const int t = c0 + i; int lo = t - H, hi = t + H - 1; lo = lo < 0 ? 0 : lo; hi = hi > SEQ - 1 ? SEQ - 1 : hi;
;         const float ic = 1.f / (float)(hi - lo + 1);
;         const u32x2 self = raw[i + H];
;         u32x2 o; o.x = pk2(s0 * ic - bflo(self.x), s1 * ic - bfhi(self.x)); o.y = pk2(s2 * ic - bflo(self.y), s3 * ic - bfhi(self.y));
;         *((u32x2*)(pl + ((size_t)J * SEQ + t) * 256) + lane) = o;
;         if (i < 7) { s0 += bflo(raw[i + W].x) - bflo(raw[i].x); s1 += bfhi(raw[i + W].x) - bfhi(raw[i].x); s2 += bflo(raw[i + W].y) - bflo(raw[i].y); s3 += bfhi(raw[i + W].y) - bfhi(raw[i].y); }
;     }
; }
; __device__ __forceinline__ void pool_phase(const Params& P) {
;     const int tid = get_tid(), wave = tid >> 6, lane = tid & 63;
;     unsigned char* ws = P.ws;
;     const int gw = get_bid() * NWAVE + wave, ngw = gridDim.x * NWAVE;
;     const bf16_t* hbuf = (const bf16_t*)(ws + O_HBUF); bf16_t* pl = (bf16_t*)(ws + O_POOL);
;     for (int c0 = gw * 8; c0 < SEQ; c0 += ngw * 8) {
	v_and_b32_e32 v18, 0xffff0000, v18
	v_add_f32_e32 v36, v36, v69
	v_add_f32_e32 v43, v43, v85
	v_lshlrev_b32_e32 v93, 16, v20
	v_and_b32_e32 v20, 0xffff0000, v20
	v_add_f32_e32 v36, v36, v18
	v_sub_f32_e32 v13, v13, v56
	v_add_f32_e32 v43, v43, v86
	v_div_fixup_f32 v45, v91, v45, 1.0
	v_lshlrev_b32_e32 v97, 16, v14
	v_and_b32_e32 v14, 0xffff0000, v14
	v_lshlrev_b32_e32 v101, 16, v38
	v_and_b32_e32 v38, 0xffff0000, v38
	v_add_f32_e32 v13, v36, v13
	v_sub_f32_e32 v20, v20, v42
	v_add_f32_e32 v43, v43, v87
	v_div_fixup_f32 v44, v95, v44, 1.0
	v_fma_f32 v58, v88, v36, -v58
	v_fma_f32 v36, v45, v13, -v82
	v_add_f32_e32 v13, v13, v20
	v_sub_f32_e32 v14, v14, v52
	v_sub_f32_e32 v38, v38, v54
	v_add_f32_e32 v43, v43, v16
	v_sub_f32_e32 v54, v90, v76
	v_lshlrev_b32_e32 v22, 16, v57
	v_and_b32_e32 v57, 0xffff0000, v57
	v_div_fixup_f32 v46, v99, v46, 1.0
	v_fma_f32 v20, v44, v13, -v61
	v_add_f32_e32 v13, v13, v14
	v_fma_f32 v52, v88, v43, -v80
	v_add_f32_e32 v43, v43, v54
	v_sub_f32_e32 v56, v93, v94
	v_add_f32_e32 v75, 0, v57
	v_lshlrev_b32_e32 v91, 16, v50
	v_and_b32_e32 v50, 0xffff0000, v50
	v_div_fixup_f32 v47, v103, v47, 1.0
	v_lshlrev_b32_e32 v109, 16, v71
	v_and_b32_e32 v71, 0xffff0000, v71
	v_fma_f32 v14, v46, v13, -v63
	v_add_f32_e32 v13, v13, v38
	v_fma_f32 v54, v45, v43, -v81
	v_add_f32_e32 v43, v43, v56
	v_sub_f32_e32 v61, v97, v98
	v_add_f32_e32 v75, v75, v50
	v_lshlrev_b32_e32 v95, 16, v53
	v_and_b32_e32 v53, 0xffff0000, v53
	v_div_fixup_f32 v48, v107, v48, 1.0
	v_and_b32_e32 v112, 0xffff0000, v73
	v_fma_f32 v38, v47, v13, -v65
	v_add_f32_e32 v13, v13, v40
	v_sub_f32_e32 v34, v71, v34
	v_fma_f32 v56, v44, v43, -v83
	v_add_f32_e32 v43, v43, v61
	v_sub_f32_e32 v63, v101, v102
	v_add_f32_e32 v75, v75, v53
	v_lshlrev_b32_e32 v99, 16, v55
	v_and_b32_e32 v55, 0xffff0000, v55
	v_fma_f32 v40, v48, v13, -v67
	v_add_f32_e32 v13, v13, v34
	v_sub_f32_e32 v42, v112, v111
	v_fma_f32 v61, v46, v43, -v84
	v_add_f32_e32 v43, v43, v63
	v_sub_f32_e32 v65, v105, v106
	v_add_f32_e32 v75, v75, v55
	v_lshlrev_b32_e32 v103, 16, v51
	v_and_b32_e32 v51, 0xffff0000, v51
	v_fma_f32 v34, v49, v13, -v69
	v_add_f32_e32 v42, v13, v42
	v_lshlrev_b32_e32 v13, 16, v73
	v_fma_f32 v63, v47, v43, -v85
	v_add_f32_e32 v43, v43, v65
	v_sub_f32_e32 v67, v109, v110
	v_add_f32_e32 v75, v75, v51
	v_lshlrev_b32_e32 v107, 16, v35
	v_and_b32_e32 v35, 0xffff0000, v35
	v_fma_f32 v65, v48, v43, -v86
	v_add_f32_e32 v43, v43, v67
	v_sub_f32_e32 v13, v13, v31
	v_add_f32_e32 v75, v75, v35
	v_add_f32_e32 v31, v43, v13
	v_and_b32_e32 v13, 0xffff0000, v30
	v_add_f32_e32 v69, v75, v13
	v_add_f32_e32 v37, v69, v37
	v_add_f32_e32 v37, v37, v59
	v_add_f32_e32 v37, v37, v60
	v_add_f32_e32 v37, v37, v62
	v_add_f32_e32 v37, v37, v64
	v_add_f32_e32 v37, v37, v66
	v_add_f32_e32 v37, v37, v68
	v_lshlrev_b32_e32 v89, 16, v12
	v_and_b32_e32 v12, 0xffff0000, v12
	v_add_f32_e32 v37, v37, v70
	v_lshlrev_b32_e32 v92, 16, v21
	v_and_b32_e32 v21, 0xffff0000, v21
	v_add_f32_e32 v37, v37, v17
	v_sub_f32_e32 v12, v12, v57
	v_add_f32_e32 v74, 0, v22
	v_lshlrev_b32_e32 v96, 16, v19
	v_and_b32_e32 v19, 0xffff0000, v19
	v_add_f32_e32 v12, v37, v12
	v_sub_f32_e32 v21, v21, v50
	v_add_f32_e32 v74, v74, v91
	v_lshlrev_b32_e32 v100, 16, v39
	v_and_b32_e32 v39, 0xffff0000, v39
	v_fma_f32 v59, v88, v37, -v59
	v_fma_f32 v37, v45, v12, -v60
	v_add_f32_e32 v12, v12, v21
	v_sub_f32_e32 v19, v19, v53
	v_add_f32_e32 v74, v74, v95
	v_lshlrev_b32_e32 v104, 16, v41
	v_and_b32_e32 v41, 0xffff0000, v41
	v_fma_f32 v21, v44, v12, -v62
	v_add_f32_e32 v12, v12, v19
	v_sub_f32_e32 v39, v39, v55
	v_add_f32_e32 v74, v74, v99
	v_lshlrev_b32_e32 v108, 16, v72
	v_and_b32_e32 v72, 0xffff0000, v72
	v_fma_f32 v19, v46, v12, -v64
	v_add_f32_e32 v12, v12, v39
	v_sub_f32_e32 v41, v41, v51
	v_add_f32_e32 v74, v74, v103
	v_fma_f32 v67, v49, v43, -v87
	v_and_b32_e32 v43, 0xffff0000, v23
	v_fma_f32 v39, v47, v12, -v66
	v_add_f32_e32 v12, v12, v41
	v_sub_f32_e32 v35, v72, v35
	v_add_f32_e32 v74, v74, v107
	v_fma_f32 v41, v48, v12, -v68
	v_add_f32_e32 v12, v12, v35
	v_sub_f32_e32 v13, v43, v13
	v_lshlrev_b32_e32 v30, 16, v30
	v_fma_f32 v35, v49, v12, -v70
	v_add_f32_e32 v43, v12, v13
	v_add_f32_e32 v12, v74, v30
	v_add_f32_e32 v12, v12, v29
	v_add_f32_e32 v12, v12, v24
	v_add_f32_e32 v12, v12, v25
	v_add_f32_e32 v12, v12, v26
	v_add_f32_e32 v12, v12, v27
	v_add_f32_e32 v12, v12, v28
	v_add_f32_e32 v12, v12, v32
	v_add_f32_e32 v12, v12, v33
	v_add_f32_e32 v12, v12, v15
	v_sub_f32_e32 v22, v89, v22
	v_fma_f32 v13, v88, v12, -v24
	v_add_f32_e32 v12, v12, v22
	v_sub_f32_e32 v24, v92, v91
	v_fma_f32 v22, v45, v12, -v25
	v_add_f32_e32 v12, v12, v24
	v_sub_f32_e32 v25, v96, v95
	v_fma_f32 v24, v44, v12, -v26
	v_add_f32_e32 v12, v12, v25
	v_sub_f32_e32 v26, v100, v99
	v_fma_f32 v25, v46, v12, -v27
	v_add_f32_e32 v12, v12, v26
	v_sub_f32_e32 v27, v104, v103
	s_mov_b32 s0, 0x4ffb9000
	v_fma_f32 v26, v47, v12, -v28
	v_add_f32_e32 v12, v12, v27
	v_sub_f32_e32 v28, v108, v107
	v_add_co_u32_e32 v10, vcc, s0, v10
	v_fma_f32 v27, v48, v12, -v32
	v_add_f32_e32 v28, v12, v28
	v_cvt_pk_bf16_f32 v12, v13, v59
	v_cvt_pk_bf16_f32 v13, v52, v58
	v_addc_co_u32_e32 v11, vcc, 0, v11, vcc
	global_store_dwordx2 v[10:11], v[12:13], off
	v_cvt_pk_bf16_f32 v13, v54, v36
	v_cvt_pk_bf16_f32 v12, v22, v37
	global_store_dwordx2 v[10:11], v[12:13], off offset:512
	v_cvt_pk_bf16_f32 v13, v56, v20
	v_cvt_pk_bf16_f32 v12, v24, v21
	global_store_dwordx2 v[10:11], v[12:13], off offset:1024
	v_cvt_pk_bf16_f32 v13, v61, v14
	v_cvt_pk_bf16_f32 v12, v25, v19
	global_store_dwordx2 v[10:11], v[12:13], off offset:1536
	v_cvt_pk_bf16_f32 v13, v63, v38
	v_cvt_pk_bf16_f32 v12, v26, v39
	global_store_dwordx2 v[10:11], v[12:13], off offset:2048
	v_cvt_pk_bf16_f32 v13, v65, v40
	v_cvt_pk_bf16_f32 v12, v27, v41
	global_store_dwordx2 v[10:11], v[12:13], off offset:2560
	v_cvt_pk_bf16_f32 v13, v67, v34
	v_fma_f32 v29, v49, v28, -v33
	v_cvt_pk_bf16_f32 v12, v29, v35
	global_store_dwordx2 v[10:11], v[12:13], off offset:3072
	v_max_i32_e32 v13, 8, v3
	v_min_i32_e32 v3, 0x3ff8, v3
	v_sub_u32_e32 v3, v3, v13
	v_add_u32_e32 v3, 16, v3
	v_cvt_f32_i32_e32 v3, v3
	v_lshlrev_b32_e32 v23, 16, v23
	v_sub_f32_e32 v12, v23, v30
	v_add_f32_e32 v12, v28, v12
	v_div_scale_f32 v13, s[0:1], v3, v3, 1.0
	v_rcp_f32_e32 v14, v13
	s_nop 0
	v_fma_f32 v19, -v13, v14, 1.0
	v_fmac_f32_e32 v14, v19, v14
	v_div_scale_f32 v19, vcc, 1.0, v3, 1.0
	v_mul_f32_e32 v20, v19, v14
	v_fma_f32 v21, -v13, v20, v19
	v_fmac_f32_e32 v20, v21, v14
	v_fma_f32 v13, -v13, v20, v19
	v_div_fmas_f32 v13, v13, v14, v20
	v_div_fixup_f32 v3, v13, v3, 1.0
	v_fma_f32 v12, v3, v12, -v15
	v_fma_f32 v13, v3, v43, -v17
	v_cmp_lt_i32_e32 vcc, s45, v2
	v_cvt_pk_bf16_f32 v12, v12, v13
	v_fma_f32 v13, v3, v31, -v16
	s_or_b64 s[48:49], vcc, s[48:49]
	v_fma_f32 v3, v3, v42, -v18
	v_cvt_pk_bf16_f32 v13, v13, v3
	global_store_dwordx2 v[10:11], v[12:13], off offset:3584
	s_andn2_b64 exec, exec, s[48:49]
	s_cbranch_execnz .LBB0_327
